# hgrn_fix: q-tile loads batched, sample rows spread over all waves; x0 loads batched
# speedup vs baseline: 1.0308x; 1.0308x over previous
; __device__ __forceinline__ int tidx() { int t = threadIdx.x; asm volatile("" : "+v"(t)); return t; }
; __device__ __forceinline__ int bidx() { int b = blockIdx.x; asm volatile("" : "+s"(b)); return b; }
; #define INP(p, i) ldp((p).tbl, i)
; __device__ void phase_x0(const Ctx& p) {
;     const int tid = tidx(); const int wave = __builtin_amdgcn_readfirstlane(tid >> 6), lane = tid & 63;
;     unsigned char* ws = uptr(p.ws);
;     float* rowss = (float*)(ws + OFF_SM + SM_ROWSS); bf16_t* XB = (bf16_t*)(ws + OFF_XB);
;     for (int row = bidx() * 8 + wave; row < T_ALL; row += gridDim.x * 8) {
;         const float* src = row < T_P ? INP(p, 0) + (size_t)row * 1024 : INP(p, 1) + (size_t)(row - T_P) * 1024;
.LBB0_17:
	s_or_b64 exec, exec, s[4:5]
	v_mov_b32_e32 v0, v184
	s_barrier
	s_mov_b32 s10, s86
	v_readfirstlane_b32 s2, v0
	s_ashr_i32 s4, s2, 6
	s_mov_b32 s11, s87
	s_mov_b32 s5, s90
	s_add_u32 s2, s10, 0x2060000
	s_addc_u32 s3, s11, 0
	s_lshl_b32 s5, s5, 3
	s_add_i32 s6, s5, s4
	s_cmpk_gt_i32 s6, 0x43ff
	v_mbcnt_lo_u32_b32 v4, -1, 0
	s_cbranch_scc1 .LBB0_26
	v_mbcnt_hi_u32_b32 v1, -1, v4
	v_and_b32_e32 v2, 64, v1
	v_add_u32_e32 v2, 64, v2
	v_xor_b32_e32 v3, 32, v1
	v_cmp_lt_i32_e32 vcc, v3, v2
	v_and_b32_e32 v0, 63, v0
	v_lshlrev_b32_e32 v12, 2, v0
	v_cndmask_b32_e32 v3, v1, v3, vcc
	v_lshlrev_b32_e32 v5, 2, v3
	v_xor_b32_e32 v3, 16, v1
	v_cmp_lt_i32_e32 vcc, v3, v2
	v_cmp_eq_u32_e64 s[4:5], 0, v0
	v_lshlrev_b32_e32 v0, 3, v0
	v_cndmask_b32_e32 v3, v1, v3, vcc
	v_lshlrev_b32_e32 v6, 2, v3
	v_xor_b32_e32 v3, 8, v1
	v_cmp_lt_i32_e32 vcc, v3, v2
	s_mov_b32 s9, 0
	s_lshl_b32 s15, s50, 3
	v_cndmask_b32_e32 v3, v1, v3, vcc
	v_lshlrev_b32_e32 v7, 2, v3
	v_xor_b32_e32 v3, 4, v1
	v_cmp_lt_i32_e32 vcc, v3, v2
	s_nop 1
	v_cndmask_b32_e32 v3, v1, v3, vcc
	v_lshlrev_b32_e32 v8, 2, v3
	v_xor_b32_e32 v3, 2, v1
	v_cmp_lt_i32_e32 vcc, v3, v2
	s_nop 1
	v_cndmask_b32_e32 v3, v1, v3, vcc
	v_lshlrev_b32_e32 v9, 2, v3
	v_xor_b32_e32 v3, 1, v1
	v_cmp_lt_i32_e32 vcc, v3, v2
	s_nop 1
	v_cndmask_b32_e32 v1, v1, v3, vcc
	v_lshlrev_b32_e32 v10, 2, v1
	v_mov_b32_e32 v1, 0
	v_lshl_add_u64 v[2:3], s[10:11], 0, v[0:1]
	s_mov_b64 s[10:11], 0x2200000
	v_lshl_add_u64 v[2:3], v[2:3], 0, s[10:11]
	v_lshlrev_b32_e32 v0, 2, v12
	v_mov_b64_e32 v[12:13], s[92:93]
	flat_load_dwordx2 v[14:15], v[12:13] sc0 sc1
	flat_load_dwordx2 v[16:17], v[12:13] offset:8 sc0 sc1
	s_waitcnt vmcnt(0) lgkmcnt(0)
	v_readfirstlane_b32 s16, v14
	v_readfirstlane_b32 s17, v15
	v_readfirstlane_b32 s18, v16
	v_readfirstlane_b32 s19, v17
	s_branch .LBB0_20

; __device__ __forceinline__ unsigned cvt_pk_bf16(float lo, float hi) { const f32x2_cv v = {lo, hi}; const bf16x2_cv b = __builtin_convertvector(v, bf16x2_cv); return __builtin_bit_cast(unsigned, b); }
; __device__ __forceinline__ int bidx() { int b = blockIdx.x; asm volatile("" : "+s"(b)); return b; }
; #define INP(p, i) ldp((p).tbl, i)
; __device__ void phase_x0(const Ctx& p) {
;     ...
;     for (int row = bidx() * 8 + wave; row < T_ALL; row += gridDim.x * 8) {
;         const float* src = row < T_P ? INP(p, 0) + (size_t)row * 1024 : INP(p, 1) + (size_t)(row - T_P) * 1024;
;         float ss = 0.f;
; #pragma unroll
;         for (int i = 0; i < 4; ++i) { const int c = i * 256 + lane * 4; const float4 v = *(const float4*)(src + c);
;             ss += v.x * v.x + v.y * v.y + v.z * v.z + v.w * v.w; u32x2 w; w.x = cvt_pk_bf16(v.x, v.y); w.y = cvt_pk_bf16(v.z, v.w); *(u32x2*)(XB + (size_t)row * 1024 + c) = w; }
;         ss = wsum(ss); if (lane == 0) rowss[row] = ss;
;     }
.LBB0_20:
	s_cmpk_gt_i32 s6, 0x3fff
	s_cbranch_scc1 .Lx0_smp
	s_ashr_i32 s7, s6, 31
	s_lshl_b64 s[10:11], s[6:7], 12
	s_add_u32 s10, s16, s10
	s_addc_u32 s11, s17, s11
	s_branch .Lx0_ld
.Lx0_smp:
	s_add_i32 s8, s6, 0xffffc000
	s_lshl_b64 s[10:11], s[8:9], 12
	s_add_u32 s10, s18, s10
	s_addc_u32 s11, s19, s11
	s_mov_b32 s7, s9
.Lx0_ld:
	global_load_dwordx4 v[12:15], v0, s[10:11]
	global_load_dwordx4 v[16:19], v0, s[10:11] offset:1024
	global_load_dwordx4 v[20:23], v0, s[10:11] offset:2048
	global_load_dwordx4 v[24:27], v0, s[10:11] offset:3072
	s_lshl_b64 s[12:13], s[6:7], 11
	v_lshl_add_u64 v[28:29], v[2:3], 0, s[12:13]
	s_waitcnt vmcnt(3)
	v_cvt_pk_bf16_f32 v30, v12, v13
	v_cvt_pk_bf16_f32 v31, v14, v15
	global_store_dwordx2 v[28:29], v[30:31], off
	v_pk_mul_f32 v[12:13], v[12:13], v[12:13]
	v_pk_mul_f32 v[14:15], v[14:15], v[14:15]
	v_add_f32_e32 v11, v12, v13
	v_add_f32_e32 v11, v11, v14
	v_add_f32_e32 v11, v11, v15
	s_waitcnt vmcnt(3)
	v_cvt_pk_bf16_f32 v30, v16, v17
	v_cvt_pk_bf16_f32 v31, v18, v19
	global_store_dwordx2 v[28:29], v[30:31], off offset:512
	v_pk_mul_f32 v[16:17], v[16:17], v[16:17]
	v_pk_mul_f32 v[18:19], v[18:19], v[18:19]
	v_add_f32_e32 v16, v16, v17
	v_add_f32_e32 v16, v16, v18
	v_add_f32_e32 v16, v16, v19
	v_add_f32_e32 v11, v11, v16
	s_waitcnt vmcnt(3)
	v_cvt_pk_bf16_f32 v30, v20, v21
	v_cvt_pk_bf16_f32 v31, v22, v23
	global_store_dwordx2 v[28:29], v[30:31], off offset:1024
	v_pk_mul_f32 v[20:21], v[20:21], v[20:21]
	v_pk_mul_f32 v[22:23], v[22:23], v[22:23]
	v_add_f32_e32 v20, v20, v21
	v_add_f32_e32 v20, v20, v22
	v_add_f32_e32 v20, v20, v23
	v_add_f32_e32 v11, v11, v20
	s_waitcnt vmcnt(3)
	v_cvt_pk_bf16_f32 v30, v24, v25
	v_cvt_pk_bf16_f32 v31, v26, v27
	global_store_dwordx2 v[28:29], v[30:31], off offset:1536
	v_pk_mul_f32 v[24:25], v[24:25], v[24:25]
	v_pk_mul_f32 v[26:27], v[26:27], v[26:27]
	v_add_f32_e32 v24, v24, v25
	v_add_f32_e32 v24, v24, v26
	v_add_f32_e32 v24, v24, v27
	v_add_f32_e32 v11, v11, v24
	ds_bpermute_b32 v12, v5, v11
	s_waitcnt lgkmcnt(0)
	v_add_f32_e32 v11, v11, v12
	ds_bpermute_b32 v12, v6, v11
	s_waitcnt lgkmcnt(0)
	v_add_f32_e32 v11, v11, v12
	ds_bpermute_b32 v12, v7, v11
	s_waitcnt lgkmcnt(0)
	v_add_f32_e32 v11, v11, v12
	ds_bpermute_b32 v12, v8, v11
	s_waitcnt lgkmcnt(0)
	v_add_f32_e32 v11, v11, v12
	ds_bpermute_b32 v12, v9, v11
	s_waitcnt lgkmcnt(0)
	v_add_f32_e32 v11, v11, v12
	ds_bpermute_b32 v12, v10, v11
	s_and_saveexec_b64 s[10:11], s[4:5]
	s_cbranch_execz .LBB0_19
	s_lshl_b64 s[12:13], s[6:7], 2
	s_add_u32 s12, s2, s12
	s_waitcnt lgkmcnt(0)
	v_add_f32_e32 v11, v11, v12
	s_addc_u32 s13, s3, s13
	global_store_dword v1, v11, s[12:13]
	s_branch .LBB0_19

; __device__ __forceinline__ float bf2f(unsigned short b) { return __uint_as_float((unsigned)b << 16); }
; __device__ __forceinline__ unsigned short f2bf(float f) { unsigned u = __float_as_uint(f); u += 0x7FFFu + ((u >> 16) & 1u); return (unsigned short)(u >> 16); }
; __device__ __forceinline__ float sigm(float x) { return __builtin_amdgcn_rcpf(1.0f + __expf(-x)); }
; __device__ void phase_hgrn_fix(const Ctx& p, int l, LAS unsigned char* lds) {
;     ...
; #pragma unroll 1
;         for (int t8 = 0; t8 < 32; t8 += 8) {
;             unsigned short rq[8][4];
; #pragma unroll
;             for (int j = 0; j < 8; ++j) { const bf16_t* r = row + (size_t)(t8 + j) * 2048; rq[j][0] = r[0]; rq[j][1] = r[64]; rq[j][2] = r[512]; rq[j][3] = r[576]; }
; #pragma unroll
;             for (int j = 0; j < 8; ++j) {
;                 const float ql = bf2f(rq[j][0]), qh = bf2f(rq[j][1]);
;                 rl *= lbl + (1.0f - lbl) * sigm(bf2f(rq[j][2])); rh *= lbh + (1.0f - lbh) * sigm(bf2f(rq[j][3]));
;                 QT[(t8 + j) * QS + lane] = f2bf(ql * sigm(ql) * rl); QT[(t8 + j) * QS + 64 + lane] = f2bf(qh * sigm(qh) * rh);
;             }
;         }
.LBB0_445:
	s_mov_b64 s[14:15], 0x1000
	v_add_co_u32_e32 v244, vcc, 0xffff8b80, v4
	s_nop 1
	v_addc_co_u32_e32 v245, vcc, -1, v5, vcc
	global_load_ushort v8, v[244:245], off
	global_load_ushort v9, v[244:245], off offset:128
	global_load_ushort v10, v[244:245], off offset:1024
	global_load_ushort v11, v[244:245], off offset:1152
	v_lshl_add_u64 v[244:245], v[244:245], 0, s[14:15]
	global_load_ushort v12, v[244:245], off
	global_load_ushort v13, v[244:245], off offset:128
	global_load_ushort v14, v[244:245], off offset:1024
	global_load_ushort v15, v[244:245], off offset:1152
	v_lshl_add_u64 v[244:245], v[244:245], 0, s[14:15]
	global_load_ushort v16, v[244:245], off
	global_load_ushort v17, v[244:245], off offset:128
	global_load_ushort v18, v[244:245], off offset:1024
	global_load_ushort v19, v[244:245], off offset:1152
	v_lshl_add_u64 v[244:245], v[244:245], 0, s[14:15]
	global_load_ushort v21, v[244:245], off
	global_load_ushort v22, v[244:245], off offset:128
	global_load_ushort v23, v[244:245], off offset:1024
	global_load_ushort v24, v[244:245], off offset:1152
	v_lshl_add_u64 v[244:245], v[244:245], 0, s[14:15]
	global_load_ushort v25, v[244:245], off
	global_load_ushort v26, v[244:245], off offset:128
	global_load_ushort v27, v[244:245], off offset:1024
	global_load_ushort v28, v[244:245], off offset:1152
	v_lshl_add_u64 v[244:245], v[244:245], 0, s[14:15]
	global_load_ushort v29, v[244:245], off
	global_load_ushort v30, v[244:245], off offset:128
	global_load_ushort v31, v[244:245], off offset:1024
	global_load_ushort v32, v[244:245], off offset:1152
	v_lshl_add_u64 v[244:245], v[244:245], 0, s[14:15]
	global_load_ushort v33, v[244:245], off
	global_load_ushort v34, v[244:245], off offset:128
	global_load_ushort v35, v[244:245], off offset:1024
	global_load_ushort v36, v[244:245], off offset:1152
	v_lshl_add_u64 v[244:245], v[244:245], 0, s[14:15]
	global_load_ushort v37, v[244:245], off
	global_load_ushort v38, v[244:245], off offset:128
	global_load_ushort v39, v[244:245], off offset:1024
	global_load_ushort v40, v[244:245], off offset:1152
	s_mov_b64 s[14:15], 0x8000
	s_add_i32 s0, s0, 8
	s_waitcnt vmcnt(28)
	v_lshlrev_b32_e32 v10, 16, v10
	v_lshlrev_b32_e32 v11, 16, v11
	v_lshlrev_b32_e32 v8, 16, v8
	v_lshlrev_b32_e32 v9, 16, v9
	v_mul_f32_e32 v246, 0xbfb8aa3b, v10
	v_mul_f32_e32 v247, 0xbfb8aa3b, v11
	v_mul_f32_e32 v250, 0xbfb8aa3b, v8
	v_mul_f32_e32 v251, 0xbfb8aa3b, v9
	v_exp_f32_e32 v246, v246
	v_exp_f32_e32 v247, v247
	v_exp_f32_e32 v250, v250
	v_exp_f32_e32 v251, v251
	v_add_f32_e32 v246, 1.0, v246
	v_add_f32_e32 v247, 1.0, v247
	v_add_f32_e32 v250, 1.0, v250
	v_add_f32_e32 v251, 1.0, v251
	v_rcp_f32_e32 v246, v246
	v_rcp_f32_e32 v247, v247
	v_rcp_f32_e32 v250, v250
	v_rcp_f32_e32 v251, v251
	v_pk_fma_f32 v[248:249], v[2:3], v[246:247], v[0:1]
	v_mul_f32_e32 v250, v250, v8
	v_mul_f32_e32 v251, v251, v9
	v_pk_mul_f32 v[6:7], v[6:7], v[248:249]
	v_mul_f32_e32 v250, v250, v6
	v_mul_f32_e32 v251, v251, v7
	v_bfe_u32 v252, v250, 16, 1
	v_bfe_u32 v253, v251, 16, 1
	v_add3_u32 v250, v250, v252, s69
	v_add3_u32 v251, v251, v253, s69
	ds_write_b16_d16_hi v20, v250
	ds_write_b16_d16_hi v20, v251 offset:128
	s_waitcnt vmcnt(24)
	v_lshlrev_b32_e32 v14, 16, v14
	v_lshlrev_b32_e32 v15, 16, v15
	v_lshlrev_b32_e32 v12, 16, v12
	v_lshlrev_b32_e32 v13, 16, v13
	v_mul_f32_e32 v246, 0xbfb8aa3b, v14
	v_mul_f32_e32 v247, 0xbfb8aa3b, v15
	v_mul_f32_e32 v250, 0xbfb8aa3b, v12
	v_mul_f32_e32 v251, 0xbfb8aa3b, v13
	v_exp_f32_e32 v246, v246
	v_exp_f32_e32 v247, v247
	v_exp_f32_e32 v250, v250
	v_exp_f32_e32 v251, v251
	v_add_f32_e32 v246, 1.0, v246
	v_add_f32_e32 v247, 1.0, v247
	v_add_f32_e32 v250, 1.0, v250
	v_add_f32_e32 v251, 1.0, v251
	v_rcp_f32_e32 v246, v246
	v_rcp_f32_e32 v247, v247
	v_rcp_f32_e32 v250, v250
	v_rcp_f32_e32 v251, v251
	v_pk_fma_f32 v[248:249], v[2:3], v[246:247], v[0:1]
	v_mul_f32_e32 v250, v250, v12
	v_mul_f32_e32 v251, v251, v13
	v_pk_mul_f32 v[6:7], v[6:7], v[248:249]
	v_mul_f32_e32 v250, v250, v6
	v_mul_f32_e32 v251, v251, v7
	v_bfe_u32 v252, v250, 16, 1
	v_bfe_u32 v253, v251, 16, 1
	v_add3_u32 v250, v250, v252, s69
	v_add3_u32 v251, v251, v253, s69
	ds_write_b16_d16_hi v20, v250 offset:272
	ds_write_b16_d16_hi v20, v251 offset:400
	s_waitcnt vmcnt(20)
	v_lshlrev_b32_e32 v18, 16, v18
	v_lshlrev_b32_e32 v19, 16, v19
	v_lshlrev_b32_e32 v16, 16, v16
	v_lshlrev_b32_e32 v17, 16, v17
	v_mul_f32_e32 v246, 0xbfb8aa3b, v18
	v_mul_f32_e32 v247, 0xbfb8aa3b, v19
	v_mul_f32_e32 v250, 0xbfb8aa3b, v16
	v_mul_f32_e32 v251, 0xbfb8aa3b, v17
	v_exp_f32_e32 v246, v246
	v_exp_f32_e32 v247, v247
	v_exp_f32_e32 v250, v250
	v_exp_f32_e32 v251, v251
	v_add_f32_e32 v246, 1.0, v246
	v_add_f32_e32 v247, 1.0, v247
	v_add_f32_e32 v250, 1.0, v250
	v_add_f32_e32 v251, 1.0, v251
	v_rcp_f32_e32 v246, v246
	v_rcp_f32_e32 v247, v247
	v_rcp_f32_e32 v250, v250
	v_rcp_f32_e32 v251, v251
	v_pk_fma_f32 v[248:249], v[2:3], v[246:247], v[0:1]
	v_mul_f32_e32 v250, v250, v16
	v_mul_f32_e32 v251, v251, v17
	v_pk_mul_f32 v[6:7], v[6:7], v[248:249]
	v_mul_f32_e32 v250, v250, v6
	v_mul_f32_e32 v251, v251, v7
	v_bfe_u32 v252, v250, 16, 1
	v_bfe_u32 v253, v251, 16, 1
	v_add3_u32 v250, v250, v252, s69
	v_add3_u32 v251, v251, v253, s69
	ds_write_b16_d16_hi v20, v250 offset:544
	ds_write_b16_d16_hi v20, v251 offset:672
	s_waitcnt vmcnt(16)
; __device__ __forceinline__ float bf2f(unsigned short b) { return __uint_as_float((unsigned)b << 16); }
; __device__ __forceinline__ unsigned short f2bf(float f) { unsigned u = __float_as_uint(f); u += 0x7FFFu + ((u >> 16) & 1u); return (unsigned short)(u >> 16); }
; __device__ __forceinline__ float sigm(float x) { return __builtin_amdgcn_rcpf(1.0f + __expf(-x)); }
; __device__ void phase_hgrn_fix(const Ctx& p, int l, LAS unsigned char* lds) {
;     ...
; #pragma unroll 1
;         for (int t8 = 0; t8 < 32; t8 += 8) {
;             unsigned short rq[8][4];
; #pragma unroll
;             for (int j = 0; j < 8; ++j) { const bf16_t* r = row + (size_t)(t8 + j) * 2048; rq[j][0] = r[0]; rq[j][1] = r[64]; rq[j][2] = r[512]; rq[j][3] = r[576]; }
; #pragma unroll
;             for (int j = 0; j < 8; ++j) {
;                 const float ql = bf2f(rq[j][0]), qh = bf2f(rq[j][1]);
;                 rl *= lbl + (1.0f - lbl) * sigm(bf2f(rq[j][2])); rh *= lbh + (1.0f - lbh) * sigm(bf2f(rq[j][3]));
;                 QT[(t8 + j) * QS + lane] = f2bf(ql * sigm(ql) * rl); QT[(t8 + j) * QS + 64 + lane] = f2bf(qh * sigm(qh) * rh);
;             }
;         }
	v_lshlrev_b32_e32 v23, 16, v23
	v_lshlrev_b32_e32 v24, 16, v24
	v_lshlrev_b32_e32 v21, 16, v21
	v_lshlrev_b32_e32 v22, 16, v22
	v_mul_f32_e32 v246, 0xbfb8aa3b, v23
	v_mul_f32_e32 v247, 0xbfb8aa3b, v24
	v_mul_f32_e32 v250, 0xbfb8aa3b, v21
	v_mul_f32_e32 v251, 0xbfb8aa3b, v22
	v_exp_f32_e32 v246, v246
	v_exp_f32_e32 v247, v247
	v_exp_f32_e32 v250, v250
	v_exp_f32_e32 v251, v251
	v_add_f32_e32 v246, 1.0, v246
	v_add_f32_e32 v247, 1.0, v247
	v_add_f32_e32 v250, 1.0, v250
	v_add_f32_e32 v251, 1.0, v251
	v_rcp_f32_e32 v246, v246
	v_rcp_f32_e32 v247, v247
	v_rcp_f32_e32 v250, v250
	v_rcp_f32_e32 v251, v251
	v_pk_fma_f32 v[248:249], v[2:3], v[246:247], v[0:1]
	v_mul_f32_e32 v250, v250, v21
	v_mul_f32_e32 v251, v251, v22
	v_pk_mul_f32 v[6:7], v[6:7], v[248:249]
	v_mul_f32_e32 v250, v250, v6
	v_mul_f32_e32 v251, v251, v7
	v_bfe_u32 v252, v250, 16, 1
	v_bfe_u32 v253, v251, 16, 1
	v_add3_u32 v250, v250, v252, s69
	v_add3_u32 v251, v251, v253, s69
	ds_write_b16_d16_hi v20, v250 offset:816
	ds_write_b16_d16_hi v20, v251 offset:944
	s_waitcnt vmcnt(12)
	v_lshlrev_b32_e32 v27, 16, v27
	v_lshlrev_b32_e32 v28, 16, v28
	v_lshlrev_b32_e32 v25, 16, v25
	v_lshlrev_b32_e32 v26, 16, v26
	v_mul_f32_e32 v246, 0xbfb8aa3b, v27
	v_mul_f32_e32 v247, 0xbfb8aa3b, v28
	v_mul_f32_e32 v250, 0xbfb8aa3b, v25
	v_mul_f32_e32 v251, 0xbfb8aa3b, v26
	v_exp_f32_e32 v246, v246
	v_exp_f32_e32 v247, v247
	v_exp_f32_e32 v250, v250
	v_exp_f32_e32 v251, v251
	v_add_f32_e32 v246, 1.0, v246
	v_add_f32_e32 v247, 1.0, v247
	v_add_f32_e32 v250, 1.0, v250
	v_add_f32_e32 v251, 1.0, v251
	v_rcp_f32_e32 v246, v246
	v_rcp_f32_e32 v247, v247
	v_rcp_f32_e32 v250, v250
	v_rcp_f32_e32 v251, v251
	v_pk_fma_f32 v[248:249], v[2:3], v[246:247], v[0:1]
	v_mul_f32_e32 v250, v250, v25
	v_mul_f32_e32 v251, v251, v26
	v_pk_mul_f32 v[6:7], v[6:7], v[248:249]
	v_mul_f32_e32 v250, v250, v6
	v_mul_f32_e32 v251, v251, v7
	v_bfe_u32 v252, v250, 16, 1
	v_bfe_u32 v253, v251, 16, 1
	v_add3_u32 v250, v250, v252, s69
	v_add3_u32 v251, v251, v253, s69
	ds_write_b16_d16_hi v20, v250 offset:1088
	ds_write_b16_d16_hi v20, v251 offset:1216
	s_waitcnt vmcnt(8)
	v_lshlrev_b32_e32 v31, 16, v31
	v_lshlrev_b32_e32 v32, 16, v32
	v_lshlrev_b32_e32 v29, 16, v29
	v_lshlrev_b32_e32 v30, 16, v30
	v_mul_f32_e32 v246, 0xbfb8aa3b, v31
	v_mul_f32_e32 v247, 0xbfb8aa3b, v32
	v_mul_f32_e32 v250, 0xbfb8aa3b, v29
	v_mul_f32_e32 v251, 0xbfb8aa3b, v30
	v_exp_f32_e32 v246, v246
	v_exp_f32_e32 v247, v247
	v_exp_f32_e32 v250, v250
	v_exp_f32_e32 v251, v251
	v_add_f32_e32 v246, 1.0, v246
	v_add_f32_e32 v247, 1.0, v247
	v_add_f32_e32 v250, 1.0, v250
	v_add_f32_e32 v251, 1.0, v251
	v_rcp_f32_e32 v246, v246
	v_rcp_f32_e32 v247, v247
	v_rcp_f32_e32 v250, v250
	v_rcp_f32_e32 v251, v251
	v_pk_fma_f32 v[248:249], v[2:3], v[246:247], v[0:1]
	v_mul_f32_e32 v250, v250, v29
	v_mul_f32_e32 v251, v251, v30
	v_pk_mul_f32 v[6:7], v[6:7], v[248:249]
	v_mul_f32_e32 v250, v250, v6
	v_mul_f32_e32 v251, v251, v7
	v_bfe_u32 v252, v250, 16, 1
	v_bfe_u32 v253, v251, 16, 1
	v_add3_u32 v250, v250, v252, s69
	v_add3_u32 v251, v251, v253, s69
	ds_write_b16_d16_hi v20, v250 offset:1360
	ds_write_b16_d16_hi v20, v251 offset:1488
	s_waitcnt vmcnt(4)
	v_lshlrev_b32_e32 v35, 16, v35
	v_lshlrev_b32_e32 v36, 16, v36
	v_lshlrev_b32_e32 v33, 16, v33
	v_lshlrev_b32_e32 v34, 16, v34
	v_mul_f32_e32 v246, 0xbfb8aa3b, v35
	v_mul_f32_e32 v247, 0xbfb8aa3b, v36
	v_mul_f32_e32 v250, 0xbfb8aa3b, v33
	v_mul_f32_e32 v251, 0xbfb8aa3b, v34
	v_exp_f32_e32 v246, v246
	v_exp_f32_e32 v247, v247
	v_exp_f32_e32 v250, v250
	v_exp_f32_e32 v251, v251
	v_add_f32_e32 v246, 1.0, v246
	v_add_f32_e32 v247, 1.0, v247
	v_add_f32_e32 v250, 1.0, v250
	v_add_f32_e32 v251, 1.0, v251
	v_rcp_f32_e32 v246, v246
	v_rcp_f32_e32 v247, v247
	v_rcp_f32_e32 v250, v250
	v_rcp_f32_e32 v251, v251
	v_pk_fma_f32 v[248:249], v[2:3], v[246:247], v[0:1]
	v_mul_f32_e32 v250, v250, v33
	v_mul_f32_e32 v251, v251, v34
	v_pk_mul_f32 v[6:7], v[6:7], v[248:249]
	v_mul_f32_e32 v250, v250, v6
	v_mul_f32_e32 v251, v251, v7
	v_bfe_u32 v252, v250, 16, 1
	v_bfe_u32 v253, v251, 16, 1
	v_add3_u32 v250, v250, v252, s69
	v_add3_u32 v251, v251, v253, s69
	ds_write_b16_d16_hi v20, v250 offset:1632
	ds_write_b16_d16_hi v20, v251 offset:1760
	s_waitcnt vmcnt(0)
	v_lshlrev_b32_e32 v39, 16, v39
	v_lshlrev_b32_e32 v40, 16, v40
	v_lshlrev_b32_e32 v37, 16, v37
	v_lshlrev_b32_e32 v38, 16, v38
	v_mul_f32_e32 v246, 0xbfb8aa3b, v39
	v_mul_f32_e32 v247, 0xbfb8aa3b, v40
	v_mul_f32_e32 v250, 0xbfb8aa3b, v37
	v_mul_f32_e32 v251, 0xbfb8aa3b, v38
	v_exp_f32_e32 v246, v246
	v_exp_f32_e32 v247, v247
	v_exp_f32_e32 v250, v250
	v_exp_f32_e32 v251, v251
	v_add_f32_e32 v246, 1.0, v246
	v_add_f32_e32 v247, 1.0, v247
	v_add_f32_e32 v250, 1.0, v250
	v_add_f32_e32 v251, 1.0, v251
	v_rcp_f32_e32 v246, v246
	v_rcp_f32_e32 v247, v247
	v_rcp_f32_e32 v250, v250
	v_rcp_f32_e32 v251, v251
	v_pk_fma_f32 v[248:249], v[2:3], v[246:247], v[0:1]
	v_mul_f32_e32 v250, v250, v37
	v_mul_f32_e32 v251, v251, v38
	v_pk_mul_f32 v[6:7], v[6:7], v[248:249]
	v_mul_f32_e32 v250, v250, v6
	v_mul_f32_e32 v251, v251, v7
	v_bfe_u32 v252, v250, 16, 1
	v_bfe_u32 v253, v251, 16, 1
	v_add3_u32 v250, v250, v252, s69
	v_add3_u32 v251, v251, v253, s69
	ds_write_b16_d16_hi v20, v250 offset:1904
	ds_write_b16_d16_hi v20, v251 offset:2032
	v_lshl_add_u64 v[4:5], v[4:5], 0, s[14:15]
	v_add_u32_e32 v20, 0x880, v20
	s_cmp_gt_u32 s0, 23
	s_cbranch_scc0 .LBB0_445
; __device__ __forceinline__ unsigned cvt_pk_bf16(float lo, float hi) { const f32x2_cv v = {lo, hi}; const bf16x2_cv b = __builtin_convertvector(v, bf16x2_cv); return __builtin_bit_cast(unsigned, b); }
; __device__ void phase_hgrn_fix(const Ctx& p, int l, LAS unsigned char* lds) {
;     ...
;         f32x4 acc[8][2];
;         const float* sb = UCH + (size_t)idx * 16384 + fr;
; #pragma unroll
;         for (int vt = 0; vt < 8; ++vt) {
;             acc[vt][0] = (f32x4){0.f, 0.f, 0.f, 0.f}; acc[vt][1] = (f32x4){0.f, 0.f, 0.f, 0.f};
; #pragma unroll
;             for (int ks = 0; ks < 4; ++ks) {
;                 const float* sp = sb + (size_t)(ks * 32 + fq * 8) * 128 + vt * 16;
;                 u32x4 w; w.x = cvt_pk_bf16(sp[0], sp[128]); w.y = cvt_pk_bf16(sp[256], sp[384]); w.z = cvt_pk_bf16(sp[512], sp[640]); w.w = cvt_pk_bf16(sp[768], sp[896]);
;                 const bf16x8 X = __builtin_bit_cast(bf16x8, w);
;                 acc[vt][0] = __builtin_amdgcn_mfma_f32_16x16x32_bf16(X, *(const LAS bf16x8*)(QT + fr * QS + ks * 32 + fq * 8), acc[vt][0], 0, 0, 0);
;                 acc[vt][1] = __builtin_amdgcn_mfma_f32_16x16x32_bf16(X, *(const LAS bf16x8*)(QT + (16 + fr) * QS + ks * 32 + fq * 8), acc[vt][1], 0, 0, 0);
;             }
;         }
	s_ashr_i32 s3, s2, 31
	s_lshl_b64 s[0:1], s[2:3], 16
	v_lshl_add_u64 v[68:69], v[118:119], 0, s[0:1]
	v_lshl_add_u64 v[70:71], v[68:69], 0, v[128:129]
	global_load_dword v0, v[70:71], off
	global_load_dword v1, v[70:71], off offset:512
	global_load_dword v2, v[70:71], off offset:1024
	global_load_dword v3, v[70:71], off offset:1536
	global_load_dword v8, v[70:71], off offset:2048
	global_load_dword v9, v[70:71], off offset:2560
	global_load_dword v10, v[70:71], off offset:3072
	global_load_dword v11, v[70:71], off offset:3584
	v_mov_b32_e32 v153, v129
	v_lshl_add_u64 v[4:5], v[68:69], 0, v[152:153]
	global_load_dword v16, v[4:5], off
	global_load_dword v18, v[4:5], off offset:512
	global_load_dword v17, v[4:5], off offset:1024
	global_load_dword v19, v[4:5], off offset:1536
	global_load_dword v20, v[4:5], off offset:2048
	global_load_dword v21, v[4:5], off offset:2560
	global_load_dword v22, v[4:5], off offset:3072
	global_load_dword v23, v[4:5], off offset:3584
	v_mov_b32_e32 v155, v129
	v_lshl_add_u64 v[4:5], v[68:69], 0, v[154:155]
	global_load_dword v32, v[4:5], off
	global_load_dword v33, v[4:5], off offset:512
	global_load_dword v34, v[4:5], off offset:1024
	global_load_dword v35, v[4:5], off offset:1536
	global_load_dword v36, v[4:5], off offset:2048
	global_load_dword v37, v[4:5], off offset:2560
	global_load_dword v38, v[4:5], off offset:3072
	global_load_dword v39, v[4:5], off offset:3584
	v_mov_b32_e32 v157, v129
	v_lshl_add_u64 v[4:5], v[68:69], 0, v[156:157]
	global_load_dword v40, v[4:5], off
	global_load_dword v41, v[4:5], off offset:512
	global_load_dword v42, v[4:5], off offset:1024
	global_load_dword v43, v[4:5], off offset:1536
	global_load_dword v60, v[4:5], off offset:2048
	global_load_dword v61, v[4:5], off offset:2560
	global_load_dword v62, v[4:5], off offset:3072
	global_load_dword v63, v[4:5], off offset:3584
	global_load_dword v64, v[70:71], off offset:64
	global_load_dword v65, v[70:71], off offset:576
	global_load_dword v66, v[70:71], off offset:1088
	global_load_dword v67, v[70:71], off offset:1600
	global_load_dword v72, v[70:71], off offset:2112
	global_load_dword v73, v[70:71], off offset:2624
	global_load_dword v74, v[70:71], off offset:3136
	global_load_dword v75, v[70:71], off offset:3648
	v_lshl_add_u64 v[28:29], v[68:69], 0, 64
	v_lshl_add_u64 v[24:25], v[28:29], 0, v[152:153]
	ds_read_b128 v[56:59], v192
	ds_read_b128 v[12:15], v192 offset:4352
	ds_read_b128 v[52:55], v192 offset:64
	ds_read_b128 v[4:7], v192 offset:4416
	ds_read_b128 v[48:51], v192 offset:128
	ds_read_b128 v[44:47], v192 offset:192
	global_load_dword v76, v[70:71], off offset:128
	global_load_dword v77, v[70:71], off offset:640
	global_load_dword v78, v[70:71], off offset:1152
	v_lshl_add_u64 v[30:31], v[28:29], 0, v[154:155]
	global_load_dword v79, v[24:25], off
	global_load_dword v80, v[24:25], off offset:512
	global_load_dword v81, v[24:25], off offset:1024
	global_load_dword v82, v[24:25], off offset:1536
	global_load_dword v83, v[24:25], off offset:2048
	global_load_dword v84, v[24:25], off offset:2560
	global_load_dword v85, v[24:25], off offset:3072
	global_load_dword v86, v[24:25], off offset:3584
	global_load_dword v87, v[30:31], off
	global_load_dword v88, v[30:31], off offset:512
	global_load_dword v89, v[30:31], off offset:1024
	global_load_dword v90, v[30:31], off offset:1536
	global_load_dword v91, v[30:31], off offset:2048
	global_load_dword v92, v[30:31], off offset:2560
	global_load_dword v93, v[30:31], off offset:3072
	global_load_dword v94, v[30:31], off offset:3584
	s_mov_b64 s[0:1], 0xc0
	s_lshl_b32 s10, s26, 1
	s_waitcnt vmcnt(57)
	v_cvt_pk_bf16_f32 v0, v0, v1
	s_waitcnt vmcnt(55)
	v_cvt_pk_bf16_f32 v1, v2, v3
	s_waitcnt vmcnt(53)
	v_cvt_pk_bf16_f32 v2, v8, v9
	s_waitcnt vmcnt(49)
	v_cvt_pk_bf16_f32 v8, v16, v18
	v_cvt_pk_bf16_f32 v3, v10, v11
	s_waitcnt vmcnt(47)
	v_cvt_pk_bf16_f32 v9, v17, v19
	s_waitcnt vmcnt(45)
	v_cvt_pk_bf16_f32 v10, v20, v21
	s_waitcnt vmcnt(43)
	v_cvt_pk_bf16_f32 v11, v22, v23
	s_waitcnt vmcnt(41)
	v_cvt_pk_bf16_f32 v20, v32, v33
	s_waitcnt lgkmcnt(5)
	v_mfma_f32_16x16x32_bf16 v[24:27], v[0:3], v[56:59], 0
	s_waitcnt vmcnt(39)
	v_cvt_pk_bf16_f32 v21, v34, v35
	s_waitcnt vmcnt(37)
	v_cvt_pk_bf16_f32 v22, v36, v37
	s_waitcnt vmcnt(35)
	v_cvt_pk_bf16_f32 v23, v38, v39
	s_waitcnt lgkmcnt(4)
	v_mfma_f32_16x16x32_bf16 v[0:3], v[0:3], v[12:15], 0
	s_waitcnt vmcnt(14)
	v_cvt_pk_bf16_f32 v32, v79, v80
	s_waitcnt vmcnt(12)
	v_cvt_pk_bf16_f32 v33, v81, v82
	s_waitcnt vmcnt(10)
	v_cvt_pk_bf16_f32 v34, v83, v84
	s_waitcnt lgkmcnt(3)
	v_mfma_f32_16x16x32_bf16 v[16:19], v[8:11], v[52:55], v[24:27]
	s_waitcnt vmcnt(8)
	v_cvt_pk_bf16_f32 v35, v85, v86
	s_nop 0
	v_lshl_add_u64 v[24:25], v[28:29], 0, v[156:157]
	global_load_dword v95, v[24:25], off
	global_load_dword v96, v[24:25], off offset:512
	global_load_dword v97, v[24:25], off offset:1024
	global_load_dword v98, v[24:25], off offset:1536
	global_load_dword v99, v[24:25], off offset:2048
	global_load_dword v100, v[24:25], off offset:2560
	global_load_dword v101, v[24:25], off offset:3072
	global_load_dword v102, v[24:25], off offset:3584
	s_waitcnt lgkmcnt(2)
	v_mfma_f32_16x16x32_bf16 v[0:3], v[8:11], v[4:7], v[0:3]
	v_cvt_pk_bf16_f32 v24, v40, v41
	v_cvt_pk_bf16_f32 v25, v42, v43
	v_cvt_pk_bf16_f32 v26, v60, v61
	s_waitcnt lgkmcnt(1)
	v_mfma_f32_16x16x32_bf16 v[8:11], v[20:23], v[48:51], v[16:19]
	v_cvt_pk_bf16_f32 v27, v62, v63
	s_waitcnt vmcnt(14)
	v_cvt_pk_bf16_f32 v40, v87, v88
	s_waitcnt vmcnt(12)
	v_cvt_pk_bf16_f32 v41, v89, v90
	ds_read_b128 v[16:19], v192 offset:4480
	global_load_dword v103, v[70:71], off offset:1664
	global_load_dword v104, v[70:71], off offset:2176
	s_waitcnt lgkmcnt(0)
; __device__ __forceinline__ unsigned cvt_pk_bf16(float lo, float hi) { const f32x2_cv v = {lo, hi}; const bf16x2_cv b = __builtin_convertvector(v, bf16x2_cv); return __builtin_bit_cast(unsigned, b); }
; __device__ void phase_hgrn_fix(const Ctx& p, int l, LAS unsigned char* lds) {
;     ...
;         f32x4 acc[8][2];
;         const float* sb = UCH + (size_t)idx * 16384 + fr;
; #pragma unroll
;         for (int vt = 0; vt < 8; ++vt) {
;             acc[vt][0] = (f32x4){0.f, 0.f, 0.f, 0.f}; acc[vt][1] = (f32x4){0.f, 0.f, 0.f, 0.f};
; #pragma unroll
;             for (int ks = 0; ks < 4; ++ks) {
;                 const float* sp = sb + (size_t)(ks * 32 + fq * 8) * 128 + vt * 16;
;                 u32x4 w; w.x = cvt_pk_bf16(sp[0], sp[128]); w.y = cvt_pk_bf16(sp[256], sp[384]); w.z = cvt_pk_bf16(sp[512], sp[640]); w.w = cvt_pk_bf16(sp[768], sp[896]);
;                 const bf16x8 X = __builtin_bit_cast(bf16x8, w);
;                 acc[vt][0] = __builtin_amdgcn_mfma_f32_16x16x32_bf16(X, *(const LAS bf16x8*)(QT + fr * QS + ks * 32 + fq * 8), acc[vt][0], 0, 0, 0);
;                 acc[vt][1] = __builtin_amdgcn_mfma_f32_16x16x32_bf16(X, *(const LAS bf16x8*)(QT + (16 + fr) * QS + ks * 32 + fq * 8), acc[vt][1], 0, 0, 0);
;             }
;         }
	v_mfma_f32_16x16x32_bf16 v[0:3], v[20:23], v[16:19], v[0:3]
	ds_read_b128 v[20:23], v192 offset:4544
	global_load_dword v105, v[70:71], off offset:2688
	global_load_dword v106, v[70:71], off offset:3200
	global_load_dword v107, v[70:71], off offset:3712
	s_waitcnt vmcnt(15)
	v_cvt_pk_bf16_f32 v42, v91, v92
	v_mfma_f32_16x16x32_bf16 v[36:39], v[24:27], v[44:47], v[8:11]
	s_waitcnt vmcnt(13)
	v_cvt_pk_bf16_f32 v43, v93, v94
	s_nop 0
	v_lshl_add_u64 v[8:9], v[68:69], 0, s[18:19]
	v_lshl_add_u64 v[10:11], v[8:9], 0, v[152:153]
	s_waitcnt lgkmcnt(0)
	v_mfma_f32_16x16x32_bf16 v[0:3], v[24:27], v[20:23], v[0:3]
	v_cvt_pk_bf16_f32 v24, v64, v65
	v_cvt_pk_bf16_f32 v25, v66, v67
	v_cvt_pk_bf16_f32 v26, v72, v73
	global_load_dword v64, v[10:11], off
	global_load_dword v65, v[10:11], off offset:512
	global_load_dword v66, v[10:11], off offset:1024
	global_load_dword v67, v[10:11], off offset:1536
	global_load_dword v72, v[10:11], off offset:2048
	global_load_dword v73, v[10:11], off offset:2560
	v_cvt_pk_bf16_f32 v27, v74, v75
	global_load_dword v74, v[10:11], off offset:3072
	global_load_dword v75, v[10:11], off offset:3584
	v_mfma_f32_16x16x32_bf16 v[28:31], v[24:27], v[56:59], 0
	v_lshl_add_u64 v[10:11], v[8:9], 0, v[154:155]
	global_load_dword v79, v[10:11], off
	global_load_dword v80, v[10:11], off offset:512
	global_load_dword v81, v[10:11], off offset:1024
	global_load_dword v82, v[10:11], off offset:1536
	global_load_dword v83, v[10:11], off offset:2048
	global_load_dword v84, v[10:11], off offset:2560
	global_load_dword v88, v[70:71], off offset:192
	global_load_dword v85, v[10:11], off offset:3072
	global_load_dword v86, v[10:11], off offset:3584
	v_mfma_f32_16x16x32_bf16 v[24:27], v[24:27], v[12:15], 0
	v_lshl_add_u64 v[8:9], v[8:9], 0, v[156:157]
	global_load_dword v89, v[70:71], off offset:704
	global_load_dword v90, v[70:71], off offset:1216
	global_load_dword v91, v[70:71], off offset:1728
	v_mfma_f32_16x16x32_bf16 v[28:31], v[32:35], v[52:55], v[28:31]
	v_mfma_f32_16x16x32_bf16 v[24:27], v[32:35], v[4:7], v[24:27]
	s_waitcnt vmcnt(29)
	v_cvt_pk_bf16_f32 v33, v97, v98
	v_mfma_f32_16x16x32_bf16 v[28:31], v[40:43], v[48:51], v[28:31]
	s_waitcnt vmcnt(27)
	v_cvt_pk_bf16_f32 v34, v99, v100
	v_cvt_pk_bf16_f32 v32, v95, v96
	s_waitcnt vmcnt(25)
	v_cvt_pk_bf16_f32 v35, v101, v102
	global_load_dword v87, v[8:9], off
	global_load_dword v92, v[8:9], off offset:512
	global_load_dword v93, v[8:9], off offset:1024
	global_load_dword v94, v[8:9], off offset:1536
	global_load_dword v95, v[8:9], off offset:2048
	global_load_dword v96, v[8:9], off offset:2560
	global_load_dword v97, v[8:9], off offset:3072
	global_load_dword v98, v[8:9], off offset:3584
	v_mfma_f32_16x16x32_bf16 v[60:63], v[32:35], v[44:47], v[28:31]
	s_nop 2
	v_cvt_pk_bf16_f32 v28, v76, v77
	s_waitcnt vmcnt(32)
	v_cvt_pk_bf16_f32 v29, v78, v103
	global_load_dword v76, v[70:71], off offset:2240
	global_load_dword v77, v[70:71], off offset:2752
	global_load_dword v78, v[70:71], off offset:3264
	global_load_dword v99, v[70:71], off offset:3776
	v_mfma_f32_16x16x32_bf16 v[24:27], v[40:43], v[16:19], v[24:27]
	v_lshl_add_u64 v[40:41], v[68:69], 0, s[0:1]
	v_lshl_add_u64 v[42:43], v[40:41], 0, v[152:153]
	s_waitcnt vmcnt(34)
	v_cvt_pk_bf16_f32 v30, v104, v105
	v_mfma_f32_16x16x32_bf16 v[8:11], v[32:35], v[20:23], v[24:27]
	s_waitcnt vmcnt(32)
	v_cvt_pk_bf16_f32 v31, v106, v107
	s_mov_b64 s[0:1], 0x100
	s_waitcnt vmcnt(30)
	v_cvt_pk_bf16_f32 v32, v64, v65
	v_mfma_f32_16x16x32_bf16 v[24:27], v[28:31], v[56:59], 0
	s_waitcnt vmcnt(28)
	v_cvt_pk_bf16_f32 v33, v66, v67
	global_load_dword v66, v[42:43], off
	global_load_dword v67, v[42:43], off offset:512
	s_waitcnt vmcnt(28)
	v_cvt_pk_bf16_f32 v34, v72, v73
	v_mfma_f32_16x16x32_bf16 v[28:31], v[28:31], v[12:15], 0
	s_waitcnt vmcnt(26)
	v_cvt_pk_bf16_f32 v35, v74, v75
	global_load_dword v74, v[42:43], off offset:1024
	global_load_dword v75, v[42:43], off offset:1536
	global_load_dword v100, v[42:43], off offset:2048
	global_load_dword v101, v[42:43], off offset:2560
	global_load_dword v102, v[42:43], off offset:3072
	global_load_dword v103, v[42:43], off offset:3584
	v_lshl_add_u64 v[42:43], v[40:41], 0, v[154:155]
	global_load_dword v104, v[42:43], off
	global_load_dword v105, v[42:43], off offset:512
	global_load_dword v106, v[42:43], off offset:1024
	global_load_dword v107, v[42:43], off offset:1536
	v_mfma_f32_16x16x32_bf16 v[24:27], v[32:35], v[52:55], v[24:27]
	v_lshl_add_u64 v[64:65], v[40:41], 0, v[156:157]
	s_waitcnt vmcnt(26)
	v_cvt_pk_bf16_f32 v40, v88, v89
	v_mfma_f32_16x16x32_bf16 v[28:31], v[32:35], v[4:7], v[28:31]
	v_cvt_pk_bf16_f32 v32, v79, v80
	v_cvt_pk_bf16_f32 v33, v81, v82
	global_load_dword v79, v[42:43], off offset:2048
	global_load_dword v80, v[42:43], off offset:2560
	global_load_dword v81, v[42:43], off offset:3072
	global_load_dword v82, v[42:43], off offset:3584
	v_cvt_pk_bf16_f32 v34, v83, v84
	global_load_dword v83, v[64:65], off
	global_load_dword v108, v[64:65], off offset:512
	global_load_dword v109, v[64:65], off offset:1024
	global_load_dword v110, v[64:65], off offset:1536
	global_load_dword v111, v[64:65], off offset:2048
	global_load_dword v112, v[64:65], off offset:2560
	v_cvt_pk_bf16_f32 v35, v85, v86
	s_waitcnt vmcnt(34)
	v_cvt_pk_bf16_f32 v41, v90, v91
	s_waitcnt vmcnt(24)
	v_cvt_pk_bf16_f32 v42, v76, v77
	v_mfma_f32_16x16x32_bf16 v[24:27], v[32:35], v[48:51], v[24:27]
	s_waitcnt vmcnt(22)
; __device__ __forceinline__ unsigned cvt_pk_bf16(float lo, float hi) { const f32x2_cv v = {lo, hi}; const bf16x2_cv b = __builtin_convertvector(v, bf16x2_cv); return __builtin_bit_cast(unsigned, b); }
; __device__ void phase_hgrn_fix(const Ctx& p, int l, LAS unsigned char* lds) {
;     ...
;         f32x4 acc[8][2];
;         const float* sb = UCH + (size_t)idx * 16384 + fr;
; #pragma unroll
;         for (int vt = 0; vt < 8; ++vt) {
;             acc[vt][0] = (f32x4){0.f, 0.f, 0.f, 0.f}; acc[vt][1] = (f32x4){0.f, 0.f, 0.f, 0.f};
; #pragma unroll
;             for (int ks = 0; ks < 4; ++ks) {
;                 const float* sp = sb + (size_t)(ks * 32 + fq * 8) * 128 + vt * 16;
;                 u32x4 w; w.x = cvt_pk_bf16(sp[0], sp[128]); w.y = cvt_pk_bf16(sp[256], sp[384]); w.z = cvt_pk_bf16(sp[512], sp[640]); w.w = cvt_pk_bf16(sp[768], sp[896]);
;                 const bf16x8 X = __builtin_bit_cast(bf16x8, w);
;                 acc[vt][0] = __builtin_amdgcn_mfma_f32_16x16x32_bf16(X, *(const LAS bf16x8*)(QT + fr * QS + ks * 32 + fq * 8), acc[vt][0], 0, 0, 0);
;                 acc[vt][1] = __builtin_amdgcn_mfma_f32_16x16x32_bf16(X, *(const LAS bf16x8*)(QT + (16 + fr) * QS + ks * 32 + fq * 8), acc[vt][1], 0, 0, 0);
;             }
;         }
	v_cvt_pk_bf16_f32 v43, v78, v99
	v_mfma_f32_16x16x32_bf16 v[28:31], v[32:35], v[16:19], v[28:31]
	v_cvt_pk_bf16_f32 v32, v87, v92
	v_cvt_pk_bf16_f32 v33, v93, v94
	v_cvt_pk_bf16_f32 v34, v95, v96
	v_cvt_pk_bf16_f32 v35, v97, v98
	global_load_dword v92, v[70:71], off offset:256
	global_load_dword v93, v[70:71], off offset:768
	global_load_dword v76, v[64:65], off offset:3072
	global_load_dword v77, v[64:65], off offset:3584
	v_mfma_f32_16x16x32_bf16 v[84:87], v[32:35], v[44:47], v[24:27]
	global_load_dword v78, v[70:71], off offset:1280
	global_load_dword v88, v[70:71], off offset:1792
	global_load_dword v89, v[70:71], off offset:2304
	global_load_dword v90, v[70:71], off offset:2816
	global_load_dword v91, v[70:71], off offset:3328
	global_load_dword v94, v[70:71], off offset:3840
	s_waitcnt vmcnt(22)
	v_cvt_pk_bf16_f32 v64, v104, v105
	v_mfma_f32_16x16x32_bf16 v[24:27], v[32:35], v[20:23], v[28:31]
	s_waitcnt vmcnt(20)
	v_cvt_pk_bf16_f32 v65, v106, v107
	v_mfma_f32_16x16x32_bf16 v[28:31], v[40:43], v[56:59], 0
	v_mfma_f32_16x16x32_bf16 v[32:35], v[40:43], v[12:15], 0
	v_cvt_pk_bf16_f32 v40, v66, v67
	v_lshl_add_u64 v[66:67], v[68:69], 0, s[0:1]
	v_lshl_add_u64 v[72:73], v[66:67], 0, v[152:153]
	global_load_dword v95, v[72:73], off
	global_load_dword v96, v[72:73], off offset:512
	global_load_dword v114, v[70:71], off offset:320
	global_load_dword v115, v[70:71], off offset:832
	global_load_dword v97, v[72:73], off offset:1024
	global_load_dword v98, v[72:73], off offset:1536
	global_load_dword v99, v[72:73], off offset:2048
	global_load_dword v104, v[72:73], off offset:2560
	global_load_dword v105, v[72:73], off offset:3072
	global_load_dword v106, v[72:73], off offset:3584
	v_lshl_add_u64 v[72:73], v[66:67], 0, v[154:155]
	global_load_dword v107, v[72:73], off
	global_load_dword v113, v[72:73], off offset:512
	global_load_dword v160, v[72:73], off offset:1024
	global_load_dword v161, v[72:73], off offset:1536
	global_load_dword v162, v[72:73], off offset:2048
	global_load_dword v163, v[72:73], off offset:2560
	global_load_dword v164, v[72:73], off offset:3072
	global_load_dword v165, v[72:73], off offset:3584
	v_lshl_add_u64 v[66:67], v[66:67], 0, v[156:157]
	v_cvt_pk_bf16_f32 v41, v74, v75
	v_cvt_pk_bf16_f32 v42, v100, v101
	v_cvt_pk_bf16_f32 v43, v102, v103
	global_load_dword v166, v[66:67], off
	global_load_dword v167, v[66:67], off offset:512
	global_load_dword v168, v[66:67], off offset:1024
	global_load_dword v169, v[66:67], off offset:1536
	global_load_dword v170, v[66:67], off offset:2048
	global_load_dword v171, v[66:67], off offset:2560
	global_load_dword v172, v[66:67], off offset:3072
	global_load_dword v173, v[66:67], off offset:3584
	s_waitcnt vmcnt(44)
	v_cvt_pk_bf16_f32 v66, v79, v80
	s_waitcnt vmcnt(42)
	v_cvt_pk_bf16_f32 v67, v81, v82
	v_mfma_f32_16x16x32_bf16 v[28:31], v[40:43], v[52:55], v[28:31]
	s_mov_b64 s[0:1], 0x140
	v_lshl_add_u64 v[72:73], v[68:69], 0, s[0:1]
	v_lshl_add_u64 v[74:75], v[72:73], 0, v[154:155]
	v_mfma_f32_16x16x32_bf16 v[32:35], v[40:43], v[4:7], v[32:35]
	global_load_dword v79, v[70:71], off offset:1344
	global_load_dword v174, v[70:71], off offset:1856
	global_load_dword v175, v[70:71], off offset:2368
	global_load_dword v176, v[70:71], off offset:2880
	global_load_dword v177, v[70:71], off offset:3392
	global_load_dword v178, v[70:71], off offset:3904
	s_waitcnt vmcnt(44)
	v_cvt_pk_bf16_f32 v41, v109, v110
	v_mfma_f32_16x16x32_bf16 v[28:31], v[64:67], v[48:51], v[28:31]
	s_waitcnt vmcnt(42)
	v_cvt_pk_bf16_f32 v42, v111, v112
	v_cvt_pk_bf16_f32 v40, v83, v108
	s_mov_b64 s[0:1], 0x180
	v_mfma_f32_16x16x32_bf16 v[32:35], v[64:67], v[16:19], v[32:35]
	v_lshl_add_u64 v[64:65], v[72:73], 0, v[152:153]
	global_load_dword v110, v[64:65], off
	global_load_dword v111, v[64:65], off offset:512
	global_load_dword v179, v[64:65], off offset:1024
	global_load_dword v180, v[64:65], off offset:1536
	global_load_dword v181, v[64:65], off offset:2048
	global_load_dword v182, v[64:65], off offset:2560
	global_load_dword v183, v[64:65], off offset:3072
	global_load_dword v196, v[64:65], off offset:3584
	global_load_dword v197, v[74:75], off
	global_load_dword v198, v[74:75], off offset:512
	global_load_dword v199, v[74:75], off offset:1024
	global_load_dword v200, v[74:75], off offset:1536
	global_load_dword v80, v[70:71], off offset:384
	global_load_dword v139, v[70:71], off offset:448
	global_load_dword v81, v[70:71], off offset:896
	v_lshl_add_u64 v[108:109], v[68:69], 0, s[0:1]
	s_lshl_b32 s0, s5, 3
	s_and_b32 s2, s0, 0xffffff80
	s_mov_b64 s[0:1], 0x1c0
	v_lshl_add_u64 v[68:69], v[68:69], 0, s[0:1]
	s_or_b32 s0, s2, s12
	s_mov_b32 s1, s11
	s_add_i32 s5, s5, s66
	s_waitcnt vmcnt(55)
	v_cvt_pk_bf16_f32 v64, v92, v93
	s_waitcnt vmcnt(53)
	v_cvt_pk_bf16_f32 v43, v76, v77
	s_waitcnt vmcnt(51)
	v_cvt_pk_bf16_f32 v65, v78, v88
	v_mfma_f32_16x16x32_bf16 v[100:103], v[40:43], v[44:47], v[28:31]
	s_waitcnt vmcnt(49)
	v_cvt_pk_bf16_f32 v66, v89, v90
	s_waitcnt vmcnt(47)
	v_cvt_pk_bf16_f32 v67, v91, v94
	s_waitcnt vmcnt(13)
; __device__ __forceinline__ unsigned cvt_pk_bf16(float lo, float hi) { const f32x2_cv v = {lo, hi}; const bf16x2_cv b = __builtin_convertvector(v, bf16x2_cv); return __builtin_bit_cast(unsigned, b); }
; __device__ void phase_hgrn_fix(const Ctx& p, int l, LAS unsigned char* lds) {
;     ...
;         f32x4 acc[8][2];
;         const float* sb = UCH + (size_t)idx * 16384 + fr;
; #pragma unroll
;         for (int vt = 0; vt < 8; ++vt) {
;             acc[vt][0] = (f32x4){0.f, 0.f, 0.f, 0.f}; acc[vt][1] = (f32x4){0.f, 0.f, 0.f, 0.f};
; #pragma unroll
;             for (int ks = 0; ks < 4; ++ks) {
;                 const float* sp = sb + (size_t)(ks * 32 + fq * 8) * 128 + vt * 16;
;                 u32x4 w; w.x = cvt_pk_bf16(sp[0], sp[128]); w.y = cvt_pk_bf16(sp[256], sp[384]); w.z = cvt_pk_bf16(sp[512], sp[640]); w.w = cvt_pk_bf16(sp[768], sp[896]);
;                 const bf16x8 X = __builtin_bit_cast(bf16x8, w);
;                 acc[vt][0] = __builtin_amdgcn_mfma_f32_16x16x32_bf16(X, *(const LAS bf16x8*)(QT + fr * QS + ks * 32 + fq * 8), acc[vt][0], 0, 0, 0);
;                 acc[vt][1] = __builtin_amdgcn_mfma_f32_16x16x32_bf16(X, *(const LAS bf16x8*)(QT + (16 + fr) * QS + ks * 32 + fq * 8), acc[vt][1], 0, 0, 0);
;             }
;         }
	v_cvt_pk_bf16_f32 v76, v110, v111
	v_mfma_f32_16x16x32_bf16 v[28:31], v[40:43], v[20:23], v[32:35]
	v_cvt_pk_bf16_f32 v40, v95, v96
	global_load_dword v88, v[74:75], off offset:2048
	global_load_dword v96, v[74:75], off offset:2560
	global_load_dword v201, v[74:75], off offset:3072
	global_load_dword v202, v[74:75], off offset:3584
	v_lshl_add_u64 v[42:43], v[72:73], 0, v[156:157]
	global_load_dword v82, v[42:43], off
	global_load_dword v83, v[42:43], off offset:512
	global_load_dword v89, v[42:43], off offset:1024
	global_load_dword v90, v[42:43], off offset:1536
	global_load_dword v91, v[42:43], off offset:2048
	global_load_dword v92, v[42:43], off offset:2560
	global_load_dword v93, v[42:43], off offset:3072
	global_load_dword v94, v[42:43], off offset:3584
	v_cvt_pk_bf16_f32 v41, v97, v98
	v_cvt_pk_bf16_f32 v42, v99, v104
	v_cvt_pk_bf16_f32 v43, v105, v106
	v_mfma_f32_16x16x32_bf16 v[32:35], v[64:67], v[56:59], 0
	v_cvt_pk_bf16_f32 v72, v107, v113
	v_cvt_pk_bf16_f32 v73, v160, v161
	v_cvt_pk_bf16_f32 v74, v162, v163
	v_mfma_f32_16x16x32_bf16 v[64:67], v[64:67], v[12:15], 0
	v_cvt_pk_bf16_f32 v75, v164, v165
	global_load_dword v151, v[70:71], off offset:960
	global_load_dword v95, v[70:71], off offset:1408
	global_load_dword v159, v[70:71], off offset:1472
	global_load_dword v97, v[70:71], off offset:1920
	global_load_dword v98, v[70:71], off offset:2432
	global_load_dword v99, v[70:71], off offset:2944
	v_mfma_f32_16x16x32_bf16 v[32:35], v[40:43], v[52:55], v[32:35]
	global_load_dword v112, v[70:71], off offset:3456
	global_load_dword v113, v[70:71], off offset:3968
	global_load_dword v160, v[70:71], off offset:1984
	s_waitcnt vmcnt(32)
	v_cvt_pk_bf16_f32 v77, v179, v180
	s_waitcnt vmcnt(30)
	v_cvt_pk_bf16_f32 v78, v181, v182
	v_mfma_f32_16x16x32_bf16 v[40:43], v[40:43], v[4:7], v[64:67]
	s_waitcnt vmcnt(13)
	v_cvt_pk_bf16_f32 v89, v89, v90
	s_nop 0
	v_cvt_pk_bf16_f32 v64, v166, v167
	v_cvt_pk_bf16_f32 v65, v168, v169
	v_cvt_pk_bf16_f32 v66, v170, v171
	v_cvt_pk_bf16_f32 v67, v172, v173
	v_mfma_f32_16x16x32_bf16 v[32:35], v[72:75], v[48:51], v[32:35]
	s_waitcnt vmcnt(11)
	v_cvt_pk_bf16_f32 v90, v91, v92
	s_waitcnt vmcnt(9)
	v_cvt_pk_bf16_f32 v91, v93, v94
	s_waitcnt vmcnt(5)
	v_cvt_pk_bf16_f32 v97, v95, v97
	v_mfma_f32_16x16x32_bf16 v[40:43], v[72:75], v[16:19], v[40:43]
	v_cvt_pk_bf16_f32 v72, v114, v115
	v_cvt_pk_bf16_f32 v73, v79, v174
	v_cvt_pk_bf16_f32 v74, v175, v176
	v_mfma_f32_16x16x32_bf16 v[104:107], v[64:67], v[44:47], v[32:35]
	v_cvt_pk_bf16_f32 v75, v177, v178
	v_cvt_pk_bf16_f32 v79, v183, v196
	s_waitcnt vmcnt(3)
	v_cvt_pk_bf16_f32 v98, v98, v99
	v_lshl_add_u64 v[32:33], v[108:109], 0, v[152:153]
	global_load_dword v114, v[32:33], off
	global_load_dword v115, v[32:33], off offset:512
	global_load_dword v164, v[32:33], off offset:1024
	global_load_dword v165, v[32:33], off offset:1536
	global_load_dword v166, v[32:33], off offset:2048
	global_load_dword v167, v[32:33], off offset:2560
	global_load_dword v168, v[32:33], off offset:3072
	global_load_dword v169, v[32:33], off offset:3584
	v_mfma_f32_16x16x32_bf16 v[32:35], v[64:67], v[20:23], v[40:43]
	global_load_dword v161, v[70:71], off offset:2496
	global_load_dword v162, v[70:71], off offset:3008
	global_load_dword v163, v[70:71], off offset:3520
	v_lshl_add_u64 v[42:43], v[108:109], 0, v[154:155]
	v_cvt_pk_bf16_f32 v40, v197, v198
	v_cvt_pk_bf16_f32 v41, v199, v200
	global_load_dword v198, v[42:43], off
	global_load_dword v199, v[42:43], off offset:512
	global_load_dword v170, v[42:43], off offset:1024
	global_load_dword v172, v[42:43], off offset:1536
	global_load_dword v171, v[42:43], off offset:2048
	global_load_dword v173, v[42:43], off offset:2560
	global_load_dword v174, v[42:43], off offset:3072
	global_load_dword v175, v[42:43], off offset:3584
	v_lshl_add_u64 v[42:43], v[108:109], 0, v[156:157]
	global_load_dword v176, v[42:43], off
	global_load_dword v177, v[42:43], off offset:512
	global_load_dword v178, v[42:43], off offset:1024
	global_load_dword v179, v[42:43], off offset:1536
	global_load_dword v180, v[42:43], off offset:2048
	global_load_dword v181, v[42:43], off offset:2560
	global_load_dword v196, v[42:43], off offset:3072
	global_load_dword v197, v[42:43], off offset:3584
	global_load_dword v200, v[70:71], off offset:4032
	v_mfma_f32_16x16x32_bf16 v[64:67], v[72:75], v[56:59], 0
	v_cvt_pk_bf16_f32 v42, v88, v96
	v_cvt_pk_bf16_f32 v43, v201, v202
	v_lshl_add_u64 v[70:71], v[68:69], 0, v[152:153]
	v_mfma_f32_16x16x32_bf16 v[64:67], v[76:79], v[52:55], v[64:67]
	global_load_dword v153, v[70:71], off
	global_load_dword v201, v[70:71], off offset:512
	global_load_dword v212, v[70:71], off offset:1024
	global_load_dword v213, v[70:71], off offset:1536
	global_load_dword v214, v[70:71], off offset:2048
	global_load_dword v215, v[70:71], off offset:2560
	global_load_dword v216, v[70:71], off offset:3072
	global_load_dword v217, v[70:71], off offset:3584
	v_cvt_pk_bf16_f32 v88, v82, v83
	v_mfma_f32_16x16x32_bf16 v[64:67], v[40:43], v[48:51], v[64:67]
	v_cvt_pk_bf16_f32 v96, v80, v81
	s_waitcnt vmcnt(37)
	v_cvt_pk_bf16_f32 v99, v112, v113
	s_waitcnt vmcnt(34)
	v_cvt_pk_bf16_f32 v92, v114, v115
	v_mfma_f32_16x16x32_bf16 v[108:111], v[88:91], v[44:47], v[64:67]
	s_waitcnt vmcnt(32)
	v_cvt_pk_bf16_f32 v93, v164, v165
	v_lshl_add_u64 v[164:165], v[120:121], 0, s[10:11]
	s_waitcnt vmcnt(30)
; __device__ __forceinline__ unsigned cvt_pk_bf16(float lo, float hi) { const f32x2_cv v = {lo, hi}; const bf16x2_cv b = __builtin_convertvector(v, bf16x2_cv); return __builtin_bit_cast(unsigned, b); }
; __device__ __forceinline__ float lo16(unsigned w) { return __uint_as_float(w << 16); }
; __device__ __forceinline__ float hi16(unsigned w) { return __uint_as_float(w & 0xffff0000u); }
; __device__ void phase_hgrn_fix(const Ctx& p, int l, LAS unsigned char* lds) {
;     ...
;         for (int vt = 0; vt < 8; ++vt) {
;             acc[vt][0] = (f32x4){0.f, 0.f, 0.f, 0.f}; acc[vt][1] = (f32x4){0.f, 0.f, 0.f, 0.f};
; #pragma unroll
;             for (int ks = 0; ks < 4; ++ks) {
;                 const float* sp = sb + (size_t)(ks * 32 + fq * 8) * 128 + vt * 16;
;                 u32x4 w; w.x = cvt_pk_bf16(sp[0], sp[128]); w.y = cvt_pk_bf16(sp[256], sp[384]); w.z = cvt_pk_bf16(sp[512], sp[640]); w.w = cvt_pk_bf16(sp[768], sp[896]);
;                 const bf16x8 X = __builtin_bit_cast(bf16x8, w);
;                 acc[vt][0] = __builtin_amdgcn_mfma_f32_16x16x32_bf16(X, *(const LAS bf16x8*)(QT + fr * QS + ks * 32 + fq * 8), acc[vt][0], 0, 0, 0);
;                 acc[vt][1] = __builtin_amdgcn_mfma_f32_16x16x32_bf16(X, *(const LAS bf16x8*)(QT + (16 + fr) * QS + ks * 32 + fq * 8), acc[vt][1], 0, 0, 0);
;             }
;         }
; #pragma unroll
;         for (int tt = 0; tt < 2; ++tt) {
;             const int t = tbase + tt * 16 + fr;
;             const bf16_t* op = OH + (size_t)t * 512 + h * 128 + 4 * fq; const bf16_t* op1 = OH1 + (size_t)t * 512 + h * 128 + 4 * fq; const bf16_t* gp = PH + (size_t)t * 2048 + 1536 + h * 128 + 4 * fq;
;             float o[8][4]; float ss = 0.f;
; #pragma unroll
;             for (int vt = 0; vt < 8; ++vt) { const u32x2 ow = *(const u32x2*)(op + vt * 16), ox = *(const u32x2*)(op1 + vt * 16);
;                 o[vt][0] = acc[vt][tt][0] + (lo16(ow.x) + lo16(ox.x)); o[vt][1] = acc[vt][tt][1] + (hi16(ow.x) + hi16(ox.x)); o[vt][2] = acc[vt][tt][2] + (lo16(ow.y) + lo16(ox.y)); o[vt][3] = acc[vt][tt][3] + (hi16(ow.y) + hi16(ox.y));
;                 ss += (o[vt][0] * o[vt][0] + o[vt][1] * o[vt][1]) + (o[vt][2] * o[vt][2] + o[vt][3] * o[vt][3]); }
;             ss += __shfl_xor(ss, 16); ss += __shfl_xor(ss, 32);
	v_cvt_pk_bf16_f32 v94, v166, v167
	v_lshl_add_u64 v[64:65], v[68:69], 0, v[154:155]
	global_load_dword v155, v[64:65], off
	global_load_dword v218, v[64:65], off offset:512
	global_load_dword v219, v[64:65], off offset:1024
	global_load_dword v220, v[64:65], off offset:1536
	global_load_dword v221, v[64:65], off offset:2048
	global_load_dword v222, v[64:65], off offset:2560
	global_load_dword v223, v[64:65], off offset:3072
	global_load_dword v224, v[64:65], off offset:3584
	v_lshl_add_u64 v[64:65], v[68:69], 0, v[156:157]
	global_load_dword v157, v[64:65], off
	global_load_dword v225, v[64:65], off offset:512
	global_load_dword v226, v[64:65], off offset:1024
	global_load_dword v227, v[64:65], off offset:1536
	global_load_dword v228, v[64:65], off offset:2048
	global_load_dword v229, v[64:65], off offset:2560
	global_load_dword v230, v[64:65], off offset:3072
	global_load_dword v231, v[64:65], off offset:3584
	s_waitcnt vmcnt(44)
	v_cvt_pk_bf16_f32 v95, v168, v169
	v_mfma_f32_16x16x32_bf16 v[64:67], v[96:99], v[56:59], 0
	v_or_b32_e32 v168, s0, v117
	s_waitcnt vmcnt(39)
	v_cvt_pk_bf16_f32 v80, v198, v199
	s_waitcnt vmcnt(37)
	v_cvt_pk_bf16_f32 v81, v170, v172
	s_waitcnt vmcnt(35)
	v_cvt_pk_bf16_f32 v82, v171, v173
	s_waitcnt vmcnt(33)
	v_cvt_pk_bf16_f32 v83, v174, v175
	v_ashrrev_i32_e32 v169, 31, v168
	v_mfma_f32_16x16x32_bf16 v[64:67], v[92:95], v[52:55], v[64:67]
	v_lshl_add_u64 v[166:167], v[122:123], 0, s[10:11]
	v_lshlrev_b64 v[182:183], 10, v[168:169]
	v_lshl_add_u64 v[202:203], v[164:165], 0, v[182:183]
	v_lshl_add_u64 v[204:205], v[166:167], 0, v[182:183]
	global_load_dwordx2 v[206:207], v[204:205], off offset:32
	global_load_dwordx2 v[208:209], v[202:203], off offset:32
	global_load_dwordx2 v[198:199], v[202:203], off offset:64
	global_load_dwordx2 v[210:211], v[204:205], off offset:64
	s_waitcnt vmcnt(35)
	v_cvt_pk_bf16_f32 v68, v176, v177
	s_waitcnt vmcnt(33)
	v_cvt_pk_bf16_f32 v69, v178, v179
	s_waitcnt vmcnt(31)
	v_cvt_pk_bf16_f32 v70, v180, v181
	s_waitcnt vmcnt(29)
	v_cvt_pk_bf16_f32 v71, v196, v197
	v_mfma_f32_16x16x32_bf16 v[64:67], v[80:83], v[48:51], v[64:67]
	global_load_dwordx2 v[176:177], v[204:205], off offset:96
	global_load_dwordx2 v[172:173], v[202:203], off offset:96
	v_lshlrev_b64 v[170:171], 12, v[168:169]
	v_mfma_f32_16x16x32_bf16 v[112:115], v[68:71], v[44:47], v[64:67]
	v_lshl_add_u64 v[170:171], s[38:39], 0, v[170:171]
	v_lshl_add_u64 v[170:171], v[170:171], 0, s[10:11]
	s_lshl_b32 s0, s26, 2
	s_nop 0
	v_cvt_pk_bf16_f32 v64, v139, v151
	v_cvt_pk_bf16_f32 v65, v159, v160
	v_cvt_pk_bf16_f32 v66, v161, v162
	s_waitcnt vmcnt(30)
	v_cvt_pk_bf16_f32 v67, v163, v200
	v_mov_b32_e32 v159, v129
	v_lshl_add_u64 v[170:171], v[170:171], 0, v[158:159]
	v_mfma_f32_16x16x32_bf16 v[160:163], v[64:67], v[56:59], 0
	s_waitcnt vmcnt(28)
	v_cvt_pk_bf16_f32 v56, v153, v201
	s_waitcnt vmcnt(26)
	v_cvt_pk_bf16_f32 v57, v212, v213
	s_waitcnt vmcnt(24)
	v_cvt_pk_bf16_f32 v58, v214, v215
	s_waitcnt vmcnt(22)
	v_cvt_pk_bf16_f32 v59, v216, v217
	global_load_dwordx2 v[196:197], v[204:205], off offset:128
	global_load_dwordx2 v[200:201], v[202:203], off offset:128
	v_mfma_f32_16x16x32_bf16 v[160:163], v[56:59], v[52:55], v[160:163]
	global_load_dwordx2 v[212:213], v[204:205], off offset:160
	global_load_dwordx2 v[214:215], v[202:203], off offset:160
	s_waitcnt vmcnt(24)
	v_cvt_pk_bf16_f32 v52, v155, v218
	v_mfma_f32_16x16x32_bf16 v[72:75], v[72:75], v[12:15], 0
	s_waitcnt vmcnt(22)
	v_cvt_pk_bf16_f32 v53, v219, v220
	global_load_dwordx2 v[216:217], v[202:203], off offset:192
	global_load_dwordx2 v[218:219], v[204:205], off offset:192
	s_waitcnt vmcnt(22)
	v_cvt_pk_bf16_f32 v54, v221, v222
	v_mfma_f32_16x16x32_bf16 v[64:67], v[64:67], v[12:15], 0
	s_waitcnt vmcnt(20)
	v_cvt_pk_bf16_f32 v55, v223, v224
	global_load_dwordx2 v[220:221], v[202:203], off
	global_load_dwordx2 v[222:223], v[204:205], off
	s_nop 0
	global_load_dwordx2 v[202:203], v[202:203], off offset:224
	s_nop 0
	global_load_dwordx2 v[204:205], v[204:205], off offset:224
	v_mfma_f32_16x16x32_bf16 v[160:163], v[52:55], v[48:51], v[160:163]
	s_waitcnt vmcnt(18)
	v_cvt_pk_bf16_f32 v50, v228, v229
	global_load_dwordx2 v[228:229], v[170:171], off offset:3072
	v_cvt_pk_bf16_f32 v48, v157, v225
	v_cvt_pk_bf16_f32 v49, v226, v227
	s_waitcnt vmcnt(17)
	v_cvt_pk_bf16_f32 v51, v230, v231
	s_waitcnt vmcnt(16)
	v_lshlrev_b32_e32 v224, 16, v206
	v_mfma_f32_16x16x32_bf16 v[44:47], v[48:51], v[44:47], v[160:163]
	s_waitcnt vmcnt(14)
	v_lshlrev_b32_e32 v175, 16, v199
	v_lshlrev_b32_e32 v174, 16, v198
	s_waitcnt vmcnt(13)
	v_lshlrev_b32_e32 v179, 16, v211
	v_lshlrev_b32_e32 v178, 16, v210
	v_pk_add_f32 v[174:175], v[174:175], v[178:179]
	v_mov_b32_e32 v178, v84
	v_mov_b32_e32 v179, v86
	v_pk_add_f32 v[180:181], v[178:179], v[174:175]
	v_and_b32_e32 v175, 0xffff0000, v199
	v_and_b32_e32 v174, 0xffff0000, v198
	v_and_b32_e32 v179, 0xffff0000, v211
	v_and_b32_e32 v178, 0xffff0000, v210
	v_pk_add_f32 v[174:175], v[174:175], v[178:179]
	v_mov_b32_e32 v86, v85
	v_pk_add_f32 v[178:179], v[86:87], v[174:175]
	s_waitcnt vmcnt(12)
	v_lshlrev_b32_e32 v86, 16, v176
	v_pk_mul_f32 v[84:85], v[178:179], v[178:179]
	v_and_b32_e32 v87, 0xffff0000, v176
	v_pk_fma_f32 v[84:85], v[180:181], v[180:181], v[84:85]
	v_lshl_add_u64 v[160:161], v[124:125], 0, s[0:1]
	v_pk_add_f32 v[210:211], v[84:85], v[84:85] op_sel:[0,1] op_sel_hi:[1,0]
	s_waitcnt vmcnt(11)
	v_lshlrev_b32_e32 v84, 16, v172
	v_and_b32_e32 v85, 0xffff0000, v172
	v_pk_add_f32 v[84:85], v[84:85], v[86:87]
	v_lshlrev_b32_e32 v86, 16, v177
	v_pk_add_f32 v[174:175], v[100:101], v[84:85]
	v_lshlrev_b32_e32 v84, 16, v173
	v_and_b32_e32 v85, 0xffff0000, v173
	v_and_b32_e32 v87, 0xffff0000, v177
	v_pk_add_f32 v[84:85], v[84:85], v[86:87]
	s_waitcnt vmcnt(10)
; __device__ __forceinline__ float lo16(unsigned w) { return __uint_as_float(w << 16); }
; __device__ __forceinline__ float hi16(unsigned w) { return __uint_as_float(w & 0xffff0000u); }
; __device__ void phase_hgrn_fix(const Ctx& p, int l, LAS unsigned char* lds) {
;     ...
; #pragma unroll
;         for (int tt = 0; tt < 2; ++tt) {
;             const int t = tbase + tt * 16 + fr;
;             const bf16_t* op = OH + (size_t)t * 512 + h * 128 + 4 * fq; const bf16_t* op1 = OH1 + (size_t)t * 512 + h * 128 + 4 * fq; const bf16_t* gp = PH + (size_t)t * 2048 + 1536 + h * 128 + 4 * fq;
;             float o[8][4]; float ss = 0.f;
; #pragma unroll
;             for (int vt = 0; vt < 8; ++vt) { const u32x2 ow = *(const u32x2*)(op + vt * 16), ox = *(const u32x2*)(op1 + vt * 16);
;                 o[vt][0] = acc[vt][tt][0] + (lo16(ow.x) + lo16(ox.x)); o[vt][1] = acc[vt][tt][1] + (hi16(ow.x) + hi16(ox.x)); o[vt][2] = acc[vt][tt][2] + (lo16(ow.y) + lo16(ox.y)); o[vt][3] = acc[vt][tt][3] + (hi16(ow.y) + hi16(ox.y));
;                 ss += (o[vt][0] * o[vt][0] + o[vt][1] * o[vt][1]) + (o[vt][2] * o[vt][2] + o[vt][3] * o[vt][3]); }
;             ss += __shfl_xor(ss, 16); ss += __shfl_xor(ss, 32);
;             const float rs = rsqrtf(ss * (1.0f / 128.0f) + 1e-6f);
	v_lshlrev_b32_e32 v86, 16, v196
	v_pk_add_f32 v[176:177], v[102:103], v[84:85]
	s_waitcnt vmcnt(9)
	v_lshlrev_b32_e32 v84, 16, v200
	v_and_b32_e32 v85, 0xffff0000, v200
	v_and_b32_e32 v87, 0xffff0000, v196
	v_pk_add_f32 v[84:85], v[84:85], v[86:87]
	v_lshlrev_b32_e32 v232, 16, v201
	v_pk_add_f32 v[172:173], v[104:105], v[84:85]
	v_and_b32_e32 v233, 0xffff0000, v201
	v_mul_f32_e32 v84, v173, v173
	v_pk_fma_f32 v[200:201], v[172:173], v[172:173], v[84:85] op_sel_hi:[1,1,0]
	v_lshl_add_u64 v[162:163], v[126:127], 0, s[10:11]
	v_lshlrev_b32_e32 v230, 16, v197
	v_and_b32_e32 v231, 0xffff0000, v197
	v_lshlrev_b32_e32 v226, 16, v208
	v_and_b32_e32 v225, 0xffff0000, v206
	v_and_b32_e32 v227, 0xffff0000, v208
	v_lshlrev_b32_e32 v206, 16, v207
	v_lshlrev_b32_e32 v208, 16, v209
	v_and_b32_e32 v207, 0xffff0000, v207
	v_and_b32_e32 v209, 0xffff0000, v209
	v_mov_b32_e32 v201, v44
	s_waitcnt vmcnt(8)
	v_lshlrev_b32_e32 v234, 16, v212
	s_waitcnt vmcnt(7)
	v_lshlrev_b32_e32 v236, 16, v214
	v_and_b32_e32 v235, 0xffff0000, v212
	v_and_b32_e32 v237, 0xffff0000, v214
	v_lshlrev_b32_e32 v212, 16, v213
	v_lshlrev_b32_e32 v214, 16, v215
	v_and_b32_e32 v213, 0xffff0000, v213
	s_waitcnt vmcnt(6)
	v_and_b32_e32 v85, 0xffff0000, v216
	s_waitcnt vmcnt(5)
	v_and_b32_e32 v84, 0xffff0000, v218
	v_add_f32_e32 v84, v84, v85
	v_add_f32_e32 v151, v113, v84
	v_and_b32_e32 v84, 0xffff0000, v219
	v_and_b32_e32 v85, 0xffff0000, v217
	v_add_f32_e32 v84, v84, v85
	v_add_f32_e32 v139, v115, v84
	s_waitcnt vmcnt(1)
	v_and_b32_e32 v85, 0xffff0000, v204
	v_and_b32_e32 v84, 0xffff0000, v202
	v_pk_add_f32 v[238:239], v[84:85], v[84:85] op_sel_hi:[0,1]
	v_lshl_add_u64 v[84:85], v[162:163], 0, v[182:183]
	global_load_dwordx4 v[196:199], v[160:161], off
	global_load_dwordx2 v[182:183], v[170:171], off offset:3104
	v_lshlrev_b32_e32 v157, 16, v219
	v_lshlrev_b32_e32 v219, 16, v204
	s_waitcnt vmcnt(2)
	v_lshlrev_b32_e32 v204, 16, v228
	v_mul_f32_e32 v86, 0xbfb8aa3b, v204
	v_exp_f32_e32 v86, v86
	v_lshlrev_b32_e32 v102, 16, v221
	v_and_b32_e32 v103, 0xffff0000, v221
	v_lshlrev_b32_e32 v104, 16, v223
	v_and_b32_e32 v105, 0xffff0000, v223
	v_lshlrev_b32_e32 v87, 16, v205
	v_and_b32_e32 v101, 0xffff0000, v205
	v_pk_add_f32 v[102:103], v[102:103], v[104:105]
	v_and_b32_e32 v205, 0xffff0000, v228
	v_pk_add_f32 v[38:39], v[38:39], v[102:103]
	v_lshlrev_b32_e32 v102, 16, v220
	v_and_b32_e32 v103, 0xffff0000, v220
	v_lshlrev_b32_e32 v104, 16, v222
	v_and_b32_e32 v105, 0xffff0000, v222
	v_add_f32_e32 v169, 1.0, v86
	v_mul_f32_e32 v86, 0xbfb8aa3b, v205
	v_pk_add_f32 v[102:103], v[102:103], v[104:105]
	v_exp_f32_e32 v228, v86
	v_mul_f32_e32 v86, v175, v175
	v_pk_add_f32 v[36:37], v[36:37], v[102:103]
	v_pk_fma_f32 v[102:103], v[174:175], v[174:175], v[86:87] op_sel_hi:[1,1,0]
	v_mul_f32_e32 v86, v177, v177
	v_lshlrev_b32_e32 v100, 16, v216
	v_lshlrev_b32_e32 v153, 16, v218
	v_lshlrev_b32_e32 v155, 16, v217
	v_lshlrev_b32_e32 v217, 16, v202
	v_pk_fma_f32 v[104:105], v[176:177], v[176:177], v[86:87] op_sel_hi:[1,1,0]
	v_lshlrev_b32_e32 v113, 16, v203
	v_mov_b32_e32 v103, v217
	v_mov_b32_e32 v105, v219
	v_add_f32_e32 v86, v153, v100
	v_and_b32_e32 v115, 0xffff0000, v203
	v_pk_add_f32 v[220:221], v[102:103], v[104:105]
	v_pk_add_f32 v[104:105], v[112:113], v[86:87]
	v_add_f32_e32 v100, v157, v155
	v_mov_b32_e32 v86, v104
	v_mov_b32_e32 v87, v46
	v_pk_add_f32 v[102:103], v[114:115], v[100:101]
	v_mul_f32_e32 v216, v151, v151
	v_pk_add_f32 v[86:87], v[86:87], v[104:105]
	v_mov_b32_e32 v46, v102
	v_mul_f32_e32 v218, v139, v139
	v_pk_add_f32 v[100:101], v[46:47], v[102:103]
	v_pk_fma_f32 v[46:47], v[104:105], v[104:105], v[216:217]
	v_pk_mul_f32 v[112:113], v[86:87], v[86:87]
	v_pk_mul_f32 v[114:115], v[100:101], v[100:101]
	v_mov_b32_e32 v47, v113
	v_pk_fma_f32 v[112:113], v[102:103], v[102:103], v[218:219]
	v_and_b32_e32 v215, 0xffff0000, v215
	v_mov_b32_e32 v113, v115
	v_pk_add_f32 v[222:223], v[46:47], v[112:113]
	v_pk_add_f32 v[46:47], v[208:209], v[206:207]
	v_mov_b32_e32 v112, v39
	v_pk_add_f32 v[46:47], v[62:63], v[46:47]
	v_mov_b32_e32 v62, v38
	v_mov_b32_e32 v113, v47
	v_mov_b32_e32 v63, v46
	v_pk_mul_f32 v[112:113], v[112:113], v[112:113]
	v_mov_b32_e32 v207, v45
	v_pk_fma_f32 v[62:63], v[62:63], v[62:63], v[112:113]
	v_pk_add_f32 v[112:113], v[226:227], v[224:225]
	v_lshlrev_b32_e32 v202, 16, v229
	v_pk_add_f32 v[114:115], v[60:61], v[112:113]
	v_mov_b32_e32 v112, v37
	v_mov_b32_e32 v113, v115
	v_mov_b32_e32 v60, v36
	v_mov_b32_e32 v61, v114
	v_pk_mul_f32 v[112:113], v[112:113], v[112:113]
	v_mul_f32_e32 v86, 0xbfb8aa3b, v202
	v_pk_fma_f32 v[60:61], v[60:61], v[60:61], v[112:113]
	v_exp_f32_e32 v86, v86
	v_pk_add_f32 v[60:61], v[60:61], v[62:63]
	v_pk_add_f32 v[62:63], v[232:233], v[230:231]
	v_pk_add_f32 v[60:61], v[60:61], v[60:61] op_sel:[0,1] op_sel_hi:[1,0]
	v_pk_add_f32 v[112:113], v[106:107], v[62:63]
	v_pk_add_f32 v[60:61], v[60:61], v[210:211]
	v_pk_mul_f32 v[62:63], v[112:113], v[112:113]
	v_mov_b32_e32 v61, v44
	v_mov_b32_e32 v216, v62
	v_mov_b32_e32 v218, v63
	v_pk_add_f32 v[62:63], v[216:217], v[218:219]
	v_pk_add_f32 v[60:61], v[60:61], v[220:221]
	v_pk_add_f32 v[62:63], v[200:201], v[62:63]
	v_and_b32_e32 v203, 0xffff0000, v229
	v_pk_add_f32 v[200:201], v[60:61], v[62:63]
	v_pk_mul_f32 v[62:63], v[60:61], v[62:63]
	v_mov_b32_e32 v105, v151
	v_mov_b32_e32 v201, v63
	v_pk_add_f32 v[62:63], v[214:215], v[212:213]
	v_mov_b32_e32 v103, v139
	v_pk_add_f32 v[106:107], v[110:111], v[62:63]
	v_pk_add_f32 v[62:63], v[236:237], v[234:235]
	v_pk_mul_f32 v[110:111], v[106:107], v[106:107]
	v_pk_add_f32 v[108:109], v[108:109], v[62:63]
	v_mov_b32_e32 v44, v110
	v_pk_mul_f32 v[62:63], v[108:109], v[108:109]
	v_readlane_b32 s0, v242, 11
	v_mov_b32_e32 v206, v62
	v_mov_b32_e32 v238, v63
	v_pk_add_f32 v[62:63], v[206:207], v[238:239]
	v_mov_b32_e32 v238, v111
	v_pk_add_f32 v[44:45], v[44:45], v[238:239]
	s_add_i32 s25, s25, s0
	v_pk_add_f32 v[110:111], v[62:63], v[44:45]
	v_pk_mul_f32 v[44:45], v[62:63], v[44:45]
	v_add_f32_e32 v62, 1.0, v228
	v_mov_b32_e32 v111, v45
	v_pk_add_f32 v[44:45], v[200:201], v[110:111]
	s_cmpk_gt_i32 s5, 0x7ff
	v_pk_add_f32 v[44:45], v[44:45], v[222:223]
	s_nop 0
	v_add_f32_e32 v45, v44, v45
	ds_bpermute_b32 v60, v193, v45
	v_rcp_f32_e32 v44, v169
	s_waitcnt lgkmcnt(0)
; __device__ __forceinline__ float sigm(float x) { return __builtin_amdgcn_rcpf(1.0f + __expf(-x)); }
; __device__ __forceinline__ float lo16(unsigned w) { return __uint_as_float(w << 16); }
; __device__ __forceinline__ float hi16(unsigned w) { return __uint_as_float(w & 0xffff0000u); }
; __device__ __forceinline__ u32x2 pack4(float a, float b, float c, float d) { u32x2 w; w.x = cvt_pk_bf16(a, b); w.y = cvt_pk_bf16(c, d); return w; }
; __device__ void phase_hgrn_fix(const Ctx& p, int l, LAS unsigned char* lds) {
;     ...
;             const float rs = rsqrtf(ss * (1.0f / 128.0f) + 1e-6f);
; #pragma unroll
;             for (int vt = 0; vt < 8; ++vt) { const u32x2 gw = *(const u32x2*)(gp + vt * 16); const float4 n4 = *(const float4*)(nw + h * 128 + vt * 16 + 4 * fq);
;                 const float g4[4] = {lo16(gw.x), hi16(gw.x), lo16(gw.y), hi16(gw.y)}, nn[4] = {n4.x, n4.y, n4.z, n4.w}; float r[4];
; #pragma unroll
;                 for (int e = 0; e < 4; ++e) r[e] = o[vt][e] * rs * nn[e] * g4[e] * sigm(g4[e]);
;                 *(u32x2*)(YB + (size_t)t * 512 + h * 128 + vt * 16 + 4 * fq) = pack4(r[0], r[1], r[2], r[3]); }
	v_add_f32_e32 v60, v45, v60
	ds_bpermute_b32 v100, v194, v60
	v_rcp_f32_e32 v45, v62
	v_add_f32_e32 v62, 1.0, v86
	v_mul_f32_e32 v86, 0xbfb8aa3b, v203
	v_exp_f32_e32 v86, v86
	s_waitcnt lgkmcnt(0)
	v_add_f32_e32 v60, v60, v100
	v_fmamk_f32 v60, v60, 0x3c000000, v187
	v_mul_f32_e32 v100, 0x4b800000, v60
	v_cmp_gt_f32_e32 vcc, s67, v60
	v_rcp_f32_e32 v110, v62
	v_add_f32_e32 v62, 1.0, v86
	v_cndmask_b32_e32 v60, v60, v100, vcc
	v_rsq_f32_e32 v60, v60
	v_rcp_f32_e32 v111, v62
	v_mul_f32_e32 v62, 0x45800000, v60
	v_cndmask_b32_e32 v60, v60, v62, vcc
	v_pk_mul_f32 v[36:37], v[36:37], v[60:61] op_sel_hi:[1,0]
	v_pk_mul_f32 v[38:39], v[38:39], v[60:61] op_sel_hi:[1,0]
	s_waitcnt vmcnt(1)
	v_pk_mul_f32 v[36:37], v[196:197], v[36:37]
	v_pk_mul_f32 v[38:39], v[198:199], v[38:39]
	v_pk_mul_f32 v[36:37], v[36:37], v[204:205]
	v_pk_mul_f32 v[38:39], v[38:39], v[202:203]
	v_pk_mul_f32 v[36:37], v[44:45], v[36:37]
	v_pk_mul_f32 v[38:39], v[110:111], v[38:39]
	v_cvt_pk_bf16_f32 v36, v36, v37
	v_cvt_pk_bf16_f32 v37, v38, v39
	global_store_dwordx2 v[84:85], v[36:37], off
	global_load_dwordx4 v[36:39], v[160:161], off offset:64
	s_nop 0
	global_load_dwordx2 v[110:111], v[170:171], off offset:3136
	s_waitcnt vmcnt(3)
	v_lshlrev_b32_e32 v196, 16, v182
	v_and_b32_e32 v197, 0xffff0000, v182
	v_mul_f32_e32 v45, 0xbfb8aa3b, v196
	v_exp_f32_e32 v62, v45
	v_mul_f32_e32 v45, 0xbfb8aa3b, v197
	v_exp_f32_e32 v86, v45
	v_lshlrev_b32_e32 v44, 16, v183
	v_add_f32_e32 v62, 1.0, v62
	v_and_b32_e32 v45, 0xffff0000, v183
	v_rcp_f32_e32 v182, v62
	v_add_f32_e32 v62, 1.0, v86
	v_mul_f32_e32 v86, 0xbfb8aa3b, v44
	v_exp_f32_e32 v86, v86
	v_mul_f32_e32 v100, 0xbfb8aa3b, v45
	v_exp_f32_e32 v100, v100
	v_rcp_f32_e32 v183, v62
	v_add_f32_e32 v62, 1.0, v86
	v_rcp_f32_e32 v198, v62
	v_add_f32_e32 v62, 1.0, v100
	v_rcp_f32_e32 v199, v62
	v_pk_mul_f32 v[114:115], v[114:115], v[60:61] op_sel_hi:[1,0]
	v_pk_mul_f32 v[46:47], v[46:47], v[60:61] op_sel_hi:[1,0]
	v_mov_b32_e32 v100, v87
	s_waitcnt vmcnt(1)
	v_pk_mul_f32 v[36:37], v[36:37], v[114:115]
	v_pk_mul_f32 v[38:39], v[38:39], v[46:47]
	v_pk_mul_f32 v[36:37], v[36:37], v[196:197]
	v_pk_mul_f32 v[38:39], v[38:39], v[44:45]
	v_pk_mul_f32 v[36:37], v[182:183], v[36:37]
	v_pk_mul_f32 v[38:39], v[198:199], v[38:39]
	v_cvt_pk_bf16_f32 v36, v36, v37
	v_cvt_pk_bf16_f32 v37, v38, v39
	global_store_dwordx2 v[84:85], v[36:37], off offset:32
	global_load_dwordx4 v[36:39], v[160:161], off offset:128
	v_mfma_f32_16x16x32_bf16 v[44:47], v[76:79], v[4:7], v[72:75]
	s_waitcnt vmcnt(2)
	v_lshlrev_b32_e32 v76, 16, v111
	v_and_b32_e32 v77, 0xffff0000, v111
	v_mul_f32_e32 v78, 0xbfb8aa3b, v77
	v_lshlrev_b32_e32 v72, 16, v110
	v_mul_f32_e32 v62, 0xbfb8aa3b, v72
	v_exp_f32_e32 v62, v62
	v_and_b32_e32 v73, 0xffff0000, v110
	v_mfma_f32_16x16x32_bf16 v[40:43], v[40:43], v[16:19], v[44:47]
	global_load_dwordx2 v[74:75], v[170:171], off offset:3168
	v_exp_f32_e32 v79, v78
	s_nop 0
	v_mul_f32_e32 v45, 0xbfb8aa3b, v73
	v_exp_f32_e32 v45, v45
	v_add_f32_e32 v44, 1.0, v62
	v_mul_f32_e32 v62, 0xbfb8aa3b, v76
	v_exp_f32_e32 v62, v62
	v_add_f32_e32 v45, 1.0, v45
	v_rcp_f32_e32 v44, v44
	v_mov_b32_e32 v46, v180
	v_mov_b32_e32 v47, v178
	v_rcp_f32_e32 v45, v45
	v_add_f32_e32 v62, 1.0, v62
	v_pk_mul_f32 v[46:47], v[46:47], v[60:61] op_sel_hi:[1,0]
	v_rcp_f32_e32 v78, v62
	v_add_f32_e32 v62, 1.0, v79
	v_mov_b32_e32 v178, v181
	v_rcp_f32_e32 v79, v62
	s_waitcnt vmcnt(1)
	v_pk_mul_f32 v[36:37], v[36:37], v[46:47]
	s_nop 0
	v_pk_mul_f32 v[36:37], v[36:37], v[72:73]
	s_nop 0
	v_pk_mul_f32 v[36:37], v[36:37], v[44:45]
	v_pk_mul_f32 v[44:45], v[178:179], v[60:61] op_sel_hi:[1,0]
	v_cvt_pk_bf16_f32 v36, v36, v37
	v_pk_mul_f32 v[38:39], v[38:39], v[44:45]
	s_nop 0
	v_pk_mul_f32 v[38:39], v[38:39], v[76:77]
	s_nop 0
	v_pk_mul_f32 v[38:39], v[38:39], v[78:79]
	global_load_dwordx2 v[78:79], v[170:171], off offset:3200
	v_cvt_pk_bf16_f32 v37, v38, v39
	global_store_dwordx2 v[84:85], v[36:37], off offset:64
	global_load_dwordx4 v[44:47], v[160:161], off offset:192
	s_waitcnt vmcnt(3)
	v_lshlrev_b32_e32 v72, 16, v74
	v_mfma_f32_16x16x32_bf16 v[36:39], v[88:91], v[20:23], v[40:43]
	v_and_b32_e32 v73, 0xffff0000, v74
	v_and_b32_e32 v77, 0xffff0000, v75
	v_pk_mul_f32 v[90:91], v[174:175], v[60:61] op_sel_hi:[1,0]
	v_mul_f32_e32 v40, 0xbfb8aa3b, v72
	v_exp_f32_e32 v62, v40
	v_mul_f32_e32 v40, 0xbfb8aa3b, v73
	v_exp_f32_e32 v76, v40
	v_mfma_f32_16x16x32_bf16 v[40:43], v[96:99], v[12:15], 0
	v_add_f32_e32 v62, 1.0, v62
	v_rcp_f32_e32 v74, v62
	v_add_f32_e32 v62, 1.0, v76
	v_lshlrev_b32_e32 v76, 16, v75
	v_mul_f32_e32 v75, 0xbfb8aa3b, v76
	v_exp_f32_e32 v86, v75
	v_mul_f32_e32 v75, 0xbfb8aa3b, v77
	v_exp_f32_e32 v89, v75
	v_rcp_f32_e32 v75, v62
	v_add_f32_e32 v62, 1.0, v86
	v_rcp_f32_e32 v88, v62
	v_add_f32_e32 v62, 1.0, v89
	v_rcp_f32_e32 v89, v62
	v_mfma_f32_16x16x32_bf16 v[40:43], v[92:95], v[4:7], v[40:43]
	s_waitcnt vmcnt(0)
	v_pk_mul_f32 v[44:45], v[90:91], v[44:45]
	s_nop 0
	v_pk_mul_f32 v[44:45], v[44:45], v[72:73]
	v_pk_mul_f32 v[72:73], v[176:177], v[60:61] op_sel_hi:[1,0]
	v_pk_mul_f32 v[44:45], v[44:45], v[74:75]
	v_pk_mul_f32 v[46:47], v[72:73], v[46:47]
	v_cvt_pk_bf16_f32 v44, v44, v45
	v_pk_mul_f32 v[46:47], v[46:47], v[76:77]
	v_lshlrev_b32_e32 v76, 16, v78
	v_pk_mul_f32 v[46:47], v[46:47], v[88:89]
	v_and_b32_e32 v77, 0xffff0000, v78
	v_cvt_pk_bf16_f32 v45, v46, v47
	global_store_dwordx2 v[84:85], v[44:45], off offset:96
	global_load_dwordx4 v[44:47], v[160:161], off offset:256
	v_mul_f32_e32 v62, 0xbfb8aa3b, v76
	v_exp_f32_e32 v62, v62
	v_mul_f32_e32 v75, 0xbfb8aa3b, v77
	v_exp_f32_e32 v86, v75
	v_lshlrev_b32_e32 v74, 16, v79
	v_and_b32_e32 v75, 0xffff0000, v79
	v_add_f32_e32 v62, 1.0, v62
	v_mul_f32_e32 v79, 0xbfb8aa3b, v74
	v_rcp_f32_e32 v78, v62
	v_add_f32_e32 v62, 1.0, v86
	v_exp_f32_e32 v86, v79
	v_mul_f32_e32 v79, 0xbfb8aa3b, v75
	v_exp_f32_e32 v89, v79
	global_load_dwordx2 v[72:73], v[170:171], off offset:3232
	v_rcp_f32_e32 v79, v62
	v_add_f32_e32 v62, 1.0, v86
	v_rcp_f32_e32 v88, v62
	v_add_f32_e32 v62, 1.0, v89
	v_pk_mul_f32 v[90:91], v[172:173], v[60:61] op_sel_hi:[1,0]
	v_rcp_f32_e32 v89, v62
	v_mfma_f32_16x16x32_bf16 v[40:43], v[80:83], v[16:19], v[40:43]
	s_waitcnt vmcnt(1)
; __device__ __forceinline__ float sigm(float x) { return __builtin_amdgcn_rcpf(1.0f + __expf(-x)); }
; __device__ __forceinline__ float lo16(unsigned w) { return __uint_as_float(w << 16); }
; __device__ __forceinline__ float hi16(unsigned w) { return __uint_as_float(w & 0xffff0000u); }
; __device__ __forceinline__ u32x2 pack4(float a, float b, float c, float d) { u32x2 w; w.x = cvt_pk_bf16(a, b); w.y = cvt_pk_bf16(c, d); return w; }
; __device__ void phase_hgrn_fix(const Ctx& p, int l, LAS unsigned char* lds) {
;     ...
; #pragma unroll
;         for (int tt = 0; tt < 2; ++tt) {
;             const int t = tbase + tt * 16 + fr;
;             const bf16_t* op = OH + (size_t)t * 512 + h * 128 + 4 * fq; const bf16_t* op1 = OH1 + (size_t)t * 512 + h * 128 + 4 * fq; const bf16_t* gp = PH + (size_t)t * 2048 + 1536 + h * 128 + 4 * fq;
;             float o[8][4]; float ss = 0.f;
; #pragma unroll
;             for (int vt = 0; vt < 8; ++vt) { const u32x2 ow = *(const u32x2*)(op + vt * 16), ox = *(const u32x2*)(op1 + vt * 16);
;                 o[vt][0] = acc[vt][tt][0] + (lo16(ow.x) + lo16(ox.x)); o[vt][1] = acc[vt][tt][1] + (hi16(ow.x) + hi16(ox.x)); o[vt][2] = acc[vt][tt][2] + (lo16(ow.y) + lo16(ox.y)); o[vt][3] = acc[vt][tt][3] + (hi16(ow.y) + hi16(ox.y));
;                 ss += (o[vt][0] * o[vt][0] + o[vt][1] * o[vt][1]) + (o[vt][2] * o[vt][2] + o[vt][3] * o[vt][3]); }
;             ss += __shfl_xor(ss, 16); ss += __shfl_xor(ss, 32);
;             const float rs = rsqrtf(ss * (1.0f / 128.0f) + 1e-6f);
; #pragma unroll
;             for (int vt = 0; vt < 8; ++vt) { const u32x2 gw = *(const u32x2*)(gp + vt * 16); const float4 n4 = *(const float4*)(nw + h * 128 + vt * 16 + 4 * fq);
;                 const float g4[4] = {lo16(gw.x), hi16(gw.x), lo16(gw.y), hi16(gw.y)}, nn[4] = {n4.x, n4.y, n4.z, n4.w}; float r[4];
; #pragma unroll
;                 for (int e = 0; e < 4; ++e) r[e] = o[vt][e] * rs * nn[e] * g4[e] * sigm(g4[e]);
;                 *(u32x2*)(YB + (size_t)t * 512 + h * 128 + vt * 16 + 4 * fq) = pack4(r[0], r[1], r[2], r[3]); }
	v_pk_mul_f32 v[44:45], v[90:91], v[44:45]
	s_nop 0
	v_pk_mul_f32 v[44:45], v[44:45], v[76:77]
	v_pk_mul_f32 v[76:77], v[112:113], v[60:61] op_sel_hi:[1,0]
	v_pk_mul_f32 v[44:45], v[44:45], v[78:79]
	v_pk_mul_f32 v[46:47], v[76:77], v[46:47]
	v_cvt_pk_bf16_f32 v44, v44, v45
	v_pk_mul_f32 v[46:47], v[46:47], v[74:75]
	v_mfma_f32_16x16x32_bf16 v[40:43], v[68:71], v[20:23], v[40:43]
	v_mul_f32_e64 v46, v46, v88
	v_mul_f32_e64 v47, v47, v89
	v_pk_mul_f32 v[70:71], v[104:105], v[60:61] op_sel_hi:[1,0]
	v_cvt_pk_bf16_f32 v45, v46, v47
	global_store_dwordx2 v[84:85], v[44:45], off offset:128
	global_load_dwordx4 v[44:47], v[160:161], off offset:320
	s_nop 0
	global_load_dwordx2 v[76:77], v[170:171], off offset:3264
	v_mfma_f32_16x16x32_bf16 v[4:7], v[56:59], v[4:7], v[64:67]
	s_waitcnt vmcnt(3)
	v_lshlrev_b32_e32 v78, 16, v72
	v_and_b32_e32 v79, 0xffff0000, v72
	v_mul_f32_e32 v62, 0xbfb8aa3b, v78
	v_exp_f32_e32 v62, v62
	v_mul_f32_e32 v72, 0xbfb8aa3b, v79
	v_exp_f32_e32 v80, v72
	v_lshlrev_b32_e32 v74, 16, v73
	v_add_f32_e32 v62, 1.0, v62
	v_rcp_f32_e32 v72, v62
	v_add_f32_e32 v62, 1.0, v80
	v_pk_mul_f32 v[80:81], v[108:109], v[60:61] op_sel_hi:[1,0]
	v_and_b32_e32 v75, 0xffff0000, v73
	v_rcp_f32_e32 v73, v62
	v_mul_f32_e32 v62, 0xbfb8aa3b, v74
	v_exp_f32_e32 v62, v62
	v_mfma_f32_16x16x32_bf16 v[4:7], v[52:55], v[16:19], v[4:7]
	v_add_f32_e32 v62, 1.0, v62
	v_mfma_f32_16x16x32_bf16 v[4:7], v[48:51], v[20:23], v[4:7]
	s_waitcnt vmcnt(1)
	v_pk_mul_f32 v[44:45], v[80:81], v[44:45]
	s_nop 0
	v_pk_mul_f32 v[44:45], v[44:45], v[78:79]
	v_mul_f32_e32 v78, 0xbfb8aa3b, v75
	v_exp_f32_e32 v78, v78
	v_pk_mul_f32 v[44:45], v[44:45], v[72:73]
	v_rcp_f32_e32 v72, v62
	v_cvt_pk_bf16_f32 v44, v44, v45
	v_add_f32_e32 v62, 1.0, v78
	v_rcp_f32_e32 v73, v62
	v_pk_mul_f32 v[78:79], v[106:107], v[60:61] op_sel_hi:[1,0]
	s_nop 0
	v_pk_mul_f32 v[46:47], v[78:79], v[46:47]
	s_nop 0
	v_pk_mul_f32 v[46:47], v[46:47], v[74:75]
	s_nop 0
	v_pk_mul_f32 v[46:47], v[46:47], v[72:73]
	s_nop 0
	v_cvt_pk_bf16_f32 v45, v46, v47
	global_store_dwordx2 v[84:85], v[44:45], off offset:160
	global_load_dwordx4 v[72:75], v[160:161], off offset:384
	s_nop 0
	global_load_dwordx2 v[44:45], v[170:171], off offset:3296
	s_waitcnt vmcnt(3)
	v_lshlrev_b32_e32 v46, 16, v76
	v_mul_f32_e32 v47, 0xbfb8aa3b, v46
	v_exp_f32_e32 v62, v47
	v_and_b32_e32 v47, 0xffff0000, v76
	v_mul_f32_e32 v68, 0xbfb8aa3b, v47
	v_exp_f32_e32 v69, v68
	v_add_f32_e32 v62, 1.0, v62
	v_rcp_f32_e32 v68, v62
	v_add_f32_e32 v62, 1.0, v69
	v_rcp_f32_e32 v69, v62
	s_waitcnt vmcnt(1)
	v_pk_mul_f32 v[70:71], v[70:71], v[72:73]
	s_nop 0
	v_pk_mul_f32 v[46:47], v[70:71], v[46:47]
	v_pk_mul_f32 v[72:73], v[102:103], v[60:61] op_sel_hi:[1,0]
	v_pk_mul_f32 v[46:47], v[46:47], v[68:69]
	v_lshlrev_b32_e32 v68, 16, v77
	v_mul_f32_e32 v62, 0xbfb8aa3b, v68
	v_and_b32_e32 v69, 0xffff0000, v77
	v_exp_f32_e32 v62, v62
	v_mul_f32_e32 v70, 0xbfb8aa3b, v69
	v_exp_f32_e32 v71, v70
	v_pk_mul_f32 v[72:73], v[72:73], v[74:75]
	v_add_f32_e32 v62, 1.0, v62
	v_rcp_f32_e32 v70, v62
	v_add_f32_e32 v62, 1.0, v71
	v_rcp_f32_e32 v71, v62
	v_pk_mul_f32 v[68:69], v[72:73], v[68:69]
	v_cvt_pk_bf16_f32 v46, v46, v47
	s_waitcnt vmcnt(0)
	v_lshlrev_b32_e32 v16, 16, v44
	v_pk_mul_f32 v[68:69], v[68:69], v[70:71]
	v_mul_f32_e32 v17, 0xbfb8aa3b, v16
	v_cvt_pk_bf16_f32 v47, v68, v69
	global_store_dwordx2 v[84:85], v[46:47], off offset:192
	global_load_dwordx4 v[68:71], v[160:161], off offset:448
	v_exp_f32_e32 v48, v17
	v_or_b32_e32 v46, 16, v168
	v_ashrrev_i32_e32 v47, 31, v46
	v_lshlrev_b64 v[12:13], 10, v[46:47]
	v_lshl_add_u64 v[74:75], v[166:167], 0, v[12:13]
	v_and_b32_e32 v17, 0xffff0000, v44
	v_add_f32_e32 v44, 1.0, v48
	v_lshl_add_u64 v[72:73], v[164:165], 0, v[12:13]
	global_load_dwordx2 v[76:77], v[74:75], off offset:32
	global_load_dwordx2 v[78:79], v[72:73], off offset:32
	global_load_dwordx2 v[80:81], v[72:73], off offset:64
	v_rcp_f32_e32 v48, v44
	v_mul_f32_e32 v44, 0xbfb8aa3b, v17
	global_load_dwordx2 v[56:57], v[74:75], off offset:64
	global_load_dwordx2 v[58:59], v[72:73], off offset:96
	v_exp_f32_e32 v44, v44
	global_load_dwordx2 v[52:53], v[74:75], off offset:96
	global_load_dwordx2 v[18:19], v[72:73], off
	global_load_dwordx2 v[14:15], v[74:75], off
	v_mov_b32_e32 v62, v61
	global_load_dwordx2 v[20:21], v[74:75], off offset:128
	global_load_dwordx2 v[22:23], v[72:73], off offset:128
	v_add_f32_e32 v44, 1.0, v44
	v_rcp_f32_e32 v49, v44
	v_pk_mul_f32 v[50:51], v[62:63], v[60:61] op_sel_hi:[1,0]
	v_lshlrev_b32_e32 v44, 16, v45
	v_and_b32_e32 v45, 0xffff0000, v45
	v_mul_f32_e32 v64, 0xbfb8aa3b, v45
	v_exp_f32_e32 v65, v64
	v_lshl_add_u64 v[12:13], v[162:163], 0, v[12:13]
	s_waitcnt vmcnt(10)
	v_pk_mul_f32 v[50:51], v[50:51], v[68:69]
	s_nop 0
	v_pk_mul_f32 v[16:17], v[50:51], v[16:17]
	global_load_dwordx2 v[50:51], v[74:75], off offset:160
	global_load_dwordx2 v[54:55], v[72:73], off offset:160
	v_pk_mul_f32 v[16:17], v[16:17], v[48:49]
	v_mul_f32_e32 v48, 0xbfb8aa3b, v44
	v_exp_f32_e32 v61, v48
	global_load_dwordx2 v[48:49], v[72:73], off offset:192
	global_load_dwordx2 v[62:63], v[74:75], off offset:192
	v_cvt_pk_bf16_f32 v16, v16, v17
	s_waitcnt vmcnt(12)
	v_lshlrev_b32_e32 v68, 16, v78
	v_add_f32_e32 v61, 1.0, v61
	v_rcp_f32_e32 v64, v61
	v_add_f32_e32 v61, 1.0, v65
	v_rcp_f32_e32 v65, v61
	v_pk_mul_f32 v[60:61], v[100:101], v[60:61] op_sel_hi:[1,0]
	v_and_b32_e32 v69, 0xffff0000, v78
	v_pk_mul_f32 v[60:61], v[60:61], v[70:71]
	v_lshlrev_b32_e32 v66, 16, v76
	v_pk_mul_f32 v[44:45], v[60:61], v[44:45]
	v_and_b32_e32 v67, 0xffff0000, v76
	v_pk_mul_f32 v[44:45], v[44:45], v[64:65]
	global_load_dwordx2 v[60:61], v[72:73], off offset:224
	global_load_dwordx2 v[64:65], v[74:75], off offset:224
	v_cvt_pk_bf16_f32 v17, v44, v45
	global_store_dwordx2 v[84:85], v[16:17], off offset:224
	v_lshlrev_b64 v[16:17], 12, v[46:47]
	v_lshl_add_u64 v[16:17], s[38:39], 0, v[16:17]
	v_lshl_add_u64 v[16:17], v[16:17], 0, s[10:11]
	v_lshl_add_u64 v[16:17], v[16:17], 0, v[158:159]
	global_load_dwordx2 v[74:75], v[16:17], off offset:3072
	s_waitcnt vmcnt(15)
; __device__ __forceinline__ float lo16(unsigned w) { return __uint_as_float(w << 16); }
; __device__ __forceinline__ float hi16(unsigned w) { return __uint_as_float(w & 0xffff0000u); }
; __device__ void phase_hgrn_fix(const Ctx& p, int l, LAS unsigned char* lds) {
;     ...
; #pragma unroll
;         for (int tt = 0; tt < 2; ++tt) {
;             const int t = tbase + tt * 16 + fr;
;             const bf16_t* op = OH + (size_t)t * 512 + h * 128 + 4 * fq; const bf16_t* op1 = OH1 + (size_t)t * 512 + h * 128 + 4 * fq; const bf16_t* gp = PH + (size_t)t * 2048 + 1536 + h * 128 + 4 * fq;
;             float o[8][4]; float ss = 0.f;
; #pragma unroll
;             for (int vt = 0; vt < 8; ++vt) { const u32x2 ow = *(const u32x2*)(op + vt * 16), ox = *(const u32x2*)(op1 + vt * 16);
;                 o[vt][0] = acc[vt][tt][0] + (lo16(ow.x) + lo16(ox.x)); o[vt][1] = acc[vt][tt][1] + (hi16(ow.x) + hi16(ox.x)); o[vt][2] = acc[vt][tt][2] + (lo16(ow.y) + lo16(ox.y)); o[vt][3] = acc[vt][tt][3] + (hi16(ow.y) + hi16(ox.y));
;                 ss += (o[vt][0] * o[vt][0] + o[vt][1] * o[vt][1]) + (o[vt][2] * o[vt][2] + o[vt][3] * o[vt][3]); }
;             ss += __shfl_xor(ss, 16); ss += __shfl_xor(ss, 32);
	v_lshlrev_b32_e32 v45, 16, v81
	v_lshlrev_b32_e32 v44, 16, v80
	s_waitcnt vmcnt(14)
	v_lshlrev_b32_e32 v47, 16, v57
	v_lshlrev_b32_e32 v46, 16, v56
	v_pk_add_f32 v[44:45], v[44:45], v[46:47]
	v_mov_b32_e32 v46, v24
	v_mov_b32_e32 v47, v26
	v_pk_add_f32 v[46:47], v[46:47], v[44:45]
	v_and_b32_e32 v45, 0xffff0000, v81
	v_and_b32_e32 v44, 0xffff0000, v80
	v_and_b32_e32 v57, 0xffff0000, v57
	v_and_b32_e32 v56, 0xffff0000, v56
	v_pk_add_f32 v[44:45], v[44:45], v[56:57]
	v_mov_b32_e32 v26, v25
	v_pk_add_f32 v[44:45], v[26:27], v[44:45]
	s_waitcnt vmcnt(13)
	v_lshlrev_b32_e32 v26, 16, v58
	v_and_b32_e32 v27, 0xffff0000, v58
	s_waitcnt vmcnt(12)
	v_lshlrev_b32_e32 v56, 16, v52
	v_and_b32_e32 v57, 0xffff0000, v52
	v_pk_add_f32 v[26:27], v[26:27], v[56:57]
	v_lshlrev_b32_e32 v52, 16, v53
	v_pk_add_f32 v[26:27], v[28:29], v[26:27]
	v_lshlrev_b32_e32 v28, 16, v59
	v_and_b32_e32 v29, 0xffff0000, v59
	v_and_b32_e32 v53, 0xffff0000, v53
	v_pk_add_f32 v[28:29], v[28:29], v[52:53]
	s_waitcnt vmcnt(8)
	v_lshlrev_b32_e32 v56, 16, v23
	v_and_b32_e32 v57, 0xffff0000, v23
	v_lshlrev_b32_e32 v52, 16, v22
	v_and_b32_e32 v53, 0xffff0000, v22
	v_lshlrev_b32_e32 v22, 16, v20
	v_and_b32_e32 v23, 0xffff0000, v20
	v_pk_add_f32 v[28:29], v[30:31], v[28:29]
	v_lshlrev_b32_e32 v30, 16, v21
	v_and_b32_e32 v31, 0xffff0000, v21
	v_pk_add_f32 v[20:21], v[52:53], v[22:23]
	v_lshlrev_b32_e32 v52, 16, v15
	v_pk_add_f32 v[22:23], v[32:33], v[20:21]
	v_and_b32_e32 v53, 0xffff0000, v15
	v_mul_f32_e32 v20, v23, v23
	v_pk_fma_f32 v[58:59], v[22:23], v[22:23], v[20:21] op_sel_hi:[1,1,0]
	v_lshlrev_b32_e32 v72, 16, v79
	v_and_b32_e32 v73, 0xffff0000, v79
	v_lshlrev_b32_e32 v70, 16, v77
	v_and_b32_e32 v71, 0xffff0000, v77
	v_lshlrev_b32_e32 v88, 16, v18
	v_and_b32_e32 v89, 0xffff0000, v18
	v_lshlrev_b32_e32 v18, 16, v14
	v_pk_mul_f32 v[24:25], v[44:45], v[44:45]
	v_mov_b32_e32 v59, v4
	v_pk_fma_f32 v[24:25], v[46:47], v[46:47], v[24:25]
	s_waitcnt vmcnt(7)
	v_lshlrev_b32_e32 v80, 16, v51
	s_waitcnt vmcnt(6)
	v_lshlrev_b32_e32 v78, 16, v54
	v_and_b32_e32 v79, 0xffff0000, v54
	v_lshlrev_b32_e32 v82, 16, v55
	s_waitcnt vmcnt(5)
	v_and_b32_e32 v21, 0xffff0000, v48
	s_waitcnt vmcnt(4)
	v_and_b32_e32 v20, 0xffff0000, v62
	v_lshlrev_b32_e32 v33, 16, v48
	v_add_f32_e32 v20, v20, v21
	v_lshlrev_b32_e32 v92, 16, v49
	v_and_b32_e32 v21, 0xffff0000, v49
	v_lshlrev_b32_e32 v48, 16, v19
	v_and_b32_e32 v49, 0xffff0000, v19
	v_pk_add_f32 v[48:49], v[48:49], v[52:53]
	v_and_b32_e32 v83, 0xffff0000, v55
	v_pk_add_f32 v[2:3], v[2:3], v[48:49]
	global_load_dwordx4 v[52:55], v[160:161], off
	global_load_dwordx2 v[48:49], v[16:17], off offset:3104
	v_and_b32_e32 v81, 0xffff0000, v51
	v_add_f32_e32 v51, v41, v20
	v_and_b32_e32 v20, 0xffff0000, v63
	v_add_f32_e32 v20, v20, v21
	v_lshlrev_b32_e32 v76, 16, v50
	v_and_b32_e32 v77, 0xffff0000, v50
	v_add_f32_e32 v50, v43, v20
	s_waitcnt vmcnt(4)
	v_and_b32_e32 v21, 0xffff0000, v64
	v_and_b32_e32 v20, 0xffff0000, v60
	v_and_b32_e32 v19, 0xffff0000, v14
	s_waitcnt vmcnt(2)
	v_lshlrev_b32_e32 v90, 16, v74
	v_mul_f32_e32 v14, 0xbfb8aa3b, v90
	v_pk_add_f32 v[86:87], v[20:21], v[20:21] op_sel_hi:[0,1]
	v_exp_f32_e32 v20, v14
	v_pk_add_f32 v[14:15], v[88:89], v[18:19]
	v_and_b32_e32 v91, 0xffff0000, v74
	v_pk_add_f32 v[0:1], v[0:1], v[14:15]
	v_mul_f32_e32 v14, 0xbfb8aa3b, v91
	v_lshlrev_b32_e32 v84, 16, v62
	v_exp_f32_e32 v89, v14
	v_mul_f32_e32 v14, v27, v27
	v_mul_f32_e32 v18, v29, v29
	v_lshlrev_b32_e32 v93, 16, v63
	v_lshlrev_b32_e32 v63, 16, v60
	v_lshlrev_b32_e32 v85, 16, v64
	v_lshlrev_b32_e32 v41, 16, v61
	v_lshlrev_b32_e32 v21, 16, v65
	v_add_f32_e32 v88, 1.0, v20
	v_pk_fma_f32 v[14:15], v[26:27], v[26:27], v[14:15] op_sel_hi:[1,1,0]
	v_pk_fma_f32 v[18:19], v[28:29], v[28:29], v[18:19] op_sel_hi:[1,1,0]
	v_add_f32_e32 v20, v84, v33
	v_and_b32_e32 v43, 0xffff0000, v61
	v_and_b32_e32 v61, 0xffff0000, v65
	v_mov_b32_e32 v15, v63
	v_mov_b32_e32 v19, v85
	v_pk_add_f32 v[20:21], v[40:41], v[20:21]
	v_add_f32_e32 v60, v93, v92
	v_lshlrev_b32_e32 v64, 16, v75
	v_and_b32_e32 v65, 0xffff0000, v75
	v_pk_add_f32 v[74:75], v[14:15], v[18:19]
	v_mov_b32_e32 v14, v20
	v_mov_b32_e32 v15, v6
	v_pk_add_f32 v[18:19], v[42:43], v[60:61]
	v_mul_f32_e32 v32, v51, v51
	v_pk_add_f32 v[14:15], v[14:15], v[20:21]
	v_mov_b32_e32 v6, v18
	v_mul_f32_e32 v62, v50, v50
	v_pk_add_f32 v[6:7], v[6:7], v[18:19]
	v_pk_fma_f32 v[32:33], v[20:21], v[20:21], v[32:33]
	v_pk_mul_f32 v[40:41], v[14:15], v[14:15]
	v_pk_mul_f32 v[42:43], v[6:7], v[6:7]
	v_mov_b32_e32 v33, v41
	v_pk_fma_f32 v[40:41], v[18:19], v[18:19], v[62:63]
	v_pk_add_f32 v[24:25], v[24:25], v[24:25] op_sel:[0,1] op_sel_hi:[1,0]
	v_mov_b32_e32 v41, v43
	v_pk_add_f32 v[60:61], v[32:33], v[40:41]
	v_pk_add_f32 v[32:33], v[72:73], v[70:71]
	v_add_f32_e32 v6, 1.0, v89
	v_pk_add_f32 v[40:41], v[10:11], v[32:33]
	v_mov_b32_e32 v32, v3
	v_mov_b32_e32 v33, v41
	v_mov_b32_e32 v10, v2
	v_mov_b32_e32 v11, v40
	v_pk_mul_f32 v[32:33], v[32:33], v[32:33]
	v_mov_b32_e32 v21, v51
	v_pk_fma_f32 v[10:11], v[10:11], v[10:11], v[32:33]
	v_pk_add_f32 v[32:33], v[68:69], v[66:67]
	v_mov_b32_e32 v19, v50
	v_pk_add_f32 v[42:43], v[8:9], v[32:33]
	v_mov_b32_e32 v32, v1
	v_mov_b32_e32 v33, v43
	v_mov_b32_e32 v8, v0
	v_mov_b32_e32 v9, v42
	v_pk_mul_f32 v[32:33], v[32:33], v[32:33]
	s_nop 0
	v_pk_fma_f32 v[8:9], v[8:9], v[8:9], v[32:33]
	s_nop 0
	v_pk_add_f32 v[8:9], v[8:9], v[10:11]
	v_pk_add_f32 v[10:11], v[56:57], v[30:31]
	v_pk_add_f32 v[8:9], v[8:9], v[8:9] op_sel:[0,1] op_sel_hi:[1,0]
	v_pk_add_f32 v[32:33], v[34:35], v[10:11]
	v_pk_add_f32 v[8:9], v[8:9], v[24:25]
	v_pk_mul_f32 v[10:11], v[32:33], v[32:33]
	v_mov_b32_e32 v9, v4
	v_mov_b32_e32 v62, v10
	v_mov_b32_e32 v84, v11
	v_pk_add_f32 v[10:11], v[62:63], v[84:85]
	v_pk_add_f32 v[8:9], v[8:9], v[74:75]
	v_pk_add_f32 v[10:11], v[58:59], v[10:11]
	s_nop 0
	v_pk_add_f32 v[34:35], v[8:9], v[10:11]
	v_pk_mul_f32 v[10:11], v[8:9], v[10:11]
	v_mul_f32_e32 v8, 0xbfb8aa3b, v64
	v_mov_b32_e32 v35, v11
	v_pk_add_f32 v[10:11], v[82:83], v[80:81]
	v_exp_f32_e32 v8, v8
	v_pk_add_f32 v[24:25], v[38:39], v[10:11]
	v_pk_add_f32 v[10:11], v[78:79], v[76:77]
	v_pk_mul_f32 v[38:39], v[24:25], v[24:25]
	v_pk_add_f32 v[30:31], v[36:37], v[10:11]
	v_mov_b32_e32 v37, v5
	v_pk_mul_f32 v[10:11], v[30:31], v[30:31]
	v_mov_b32_e32 v4, v38
	v_mov_b32_e32 v36, v10
	v_mov_b32_e32 v86, v11
	v_pk_add_f32 v[10:11], v[36:37], v[86:87]
	v_mov_b32_e32 v86, v39
	v_pk_add_f32 v[4:5], v[4:5], v[86:87]
	s_waitcnt vmcnt(0)
; __device__ __forceinline__ float sigm(float x) { return __builtin_amdgcn_rcpf(1.0f + __expf(-x)); }
; __device__ __forceinline__ float lo16(unsigned w) { return __uint_as_float(w << 16); }
; __device__ __forceinline__ float hi16(unsigned w) { return __uint_as_float(w & 0xffff0000u); }
; __device__ __forceinline__ u32x2 pack4(float a, float b, float c, float d) { u32x2 w; w.x = cvt_pk_bf16(a, b); w.y = cvt_pk_bf16(c, d); return w; }
; __device__ void phase_hgrn_fix(const Ctx& p, int l, LAS unsigned char* lds) {
;     ...
;             ss += __shfl_xor(ss, 16); ss += __shfl_xor(ss, 32);
;             const float rs = rsqrtf(ss * (1.0f / 128.0f) + 1e-6f);
; #pragma unroll
;             for (int vt = 0; vt < 8; ++vt) { const u32x2 gw = *(const u32x2*)(gp + vt * 16); const float4 n4 = *(const float4*)(nw + h * 128 + vt * 16 + 4 * fq);
;                 const float g4[4] = {lo16(gw.x), hi16(gw.x), lo16(gw.y), hi16(gw.y)}, nn[4] = {n4.x, n4.y, n4.z, n4.w}; float r[4];
; #pragma unroll
;                 for (int e = 0; e < 4; ++e) r[e] = o[vt][e] * rs * nn[e] * g4[e] * sigm(g4[e]);
;                 *(u32x2*)(YB + (size_t)t * 512 + h * 128 + vt * 16 + 4 * fq) = pack4(r[0], r[1], r[2], r[3]); }
	v_lshlrev_b32_e32 v38, 16, v48
	v_pk_add_f32 v[36:37], v[10:11], v[4:5]
	v_pk_mul_f32 v[4:5], v[10:11], v[4:5]
	v_and_b32_e32 v39, 0xffff0000, v48
	v_mov_b32_e32 v37, v5
	v_pk_add_f32 v[4:5], v[34:35], v[36:37]
	v_rcp_f32_e32 v35, v6
	v_pk_add_f32 v[4:5], v[4:5], v[60:61]
	v_add_f32_e32 v6, 1.0, v8
	v_add_f32_e32 v4, v4, v5
	ds_bpermute_b32 v5, v193, v4
	v_mul_f32_e32 v8, 0xbfb8aa3b, v65
	v_exp_f32_e32 v8, v8
	v_rcp_f32_e32 v34, v88
	v_rcp_f32_e32 v36, v6
	s_waitcnt lgkmcnt(0)
	v_add_f32_e32 v4, v4, v5
	ds_bpermute_b32 v5, v194, v4
	v_mul_f32_e32 v6, 0xbfb8aa3b, v39
	v_exp_f32_e32 v6, v6
	v_mov_b32_e32 v10, v9
	s_waitcnt lgkmcnt(0)
	v_add_f32_e32 v4, v4, v5
	v_fmamk_f32 v4, v4, 0x3c000000, v187
	v_mul_f32_e32 v5, 0x4b800000, v4
	v_cmp_gt_f32_e32 vcc, s67, v4
	s_nop 1
	v_cndmask_b32_e32 v4, v4, v5, vcc
	v_rsq_f32_e32 v4, v4
	v_add_f32_e32 v5, 1.0, v8
	v_rcp_f32_e32 v37, v5
	v_mul_f32_e32 v5, 0x45800000, v4
	v_cndmask_b32_e32 v4, v4, v5, vcc
	v_pk_mul_f32 v[0:1], v[0:1], v[4:5] op_sel_hi:[1,0]
	v_pk_mul_f32 v[2:3], v[2:3], v[4:5] op_sel_hi:[1,0]
	v_pk_mul_f32 v[0:1], v[52:53], v[0:1]
	v_pk_mul_f32 v[2:3], v[54:55], v[2:3]
	v_pk_mul_f32 v[0:1], v[0:1], v[90:91]
	v_pk_mul_f32 v[2:3], v[2:3], v[64:65]
	v_pk_mul_f32 v[0:1], v[34:35], v[0:1]
	v_pk_mul_f32 v[2:3], v[36:37], v[2:3]
	v_cvt_pk_bf16_f32 v0, v0, v1
	v_cvt_pk_bf16_f32 v1, v2, v3
	global_store_dwordx2 v[12:13], v[0:1], off
	global_load_dwordx4 v[0:3], v[160:161], off offset:64
	s_nop 0
	global_load_dwordx2 v[34:35], v[16:17], off offset:3136
	v_mul_f32_e32 v5, 0xbfb8aa3b, v38
	v_exp_f32_e32 v5, v5
	v_lshlrev_b32_e32 v36, 16, v49
	v_and_b32_e32 v37, 0xffff0000, v49
	v_mul_f32_e32 v8, 0xbfb8aa3b, v37
	v_add_f32_e32 v5, 1.0, v5
	v_rcp_f32_e32 v48, v5
	v_add_f32_e32 v5, 1.0, v6
	v_mul_f32_e32 v6, 0xbfb8aa3b, v36
	v_exp_f32_e32 v6, v6
	v_exp_f32_e32 v8, v8
	v_rcp_f32_e32 v49, v5
	v_add_f32_e32 v5, 1.0, v6
	v_rcp_f32_e32 v52, v5
	v_add_f32_e32 v5, 1.0, v8
	v_pk_mul_f32 v[42:43], v[42:43], v[4:5] op_sel_hi:[1,0]
	v_rcp_f32_e32 v53, v5
	s_waitcnt vmcnt(1)
	v_pk_mul_f32 v[0:1], v[0:1], v[42:43]
	s_nop 0
	v_pk_mul_f32 v[0:1], v[0:1], v[38:39]
	v_pk_mul_f32 v[38:39], v[40:41], v[4:5] op_sel_hi:[1,0]
	v_pk_mul_f32 v[0:1], v[48:49], v[0:1]
	v_pk_mul_f32 v[2:3], v[2:3], v[38:39]
	v_cvt_pk_bf16_f32 v0, v0, v1
	v_pk_mul_f32 v[2:3], v[2:3], v[36:37]
	s_waitcnt vmcnt(0)
	v_lshlrev_b32_e32 v36, 16, v34
	v_pk_mul_f32 v[2:3], v[52:53], v[2:3]
	v_mul_f32_e32 v5, 0xbfb8aa3b, v36
	v_cvt_pk_bf16_f32 v1, v2, v3
	global_store_dwordx2 v[12:13], v[0:1], off offset:32
	global_load_dwordx4 v[0:3], v[160:161], off offset:128
	v_and_b32_e32 v37, 0xffff0000, v34
	v_exp_f32_e32 v5, v5
	v_mul_f32_e32 v6, 0xbfb8aa3b, v37
	v_exp_f32_e32 v6, v6
	v_lshlrev_b32_e32 v34, 16, v35
	v_add_f32_e32 v5, 1.0, v5
	v_rcp_f32_e32 v40, v5
	v_add_f32_e32 v5, 1.0, v6
	global_load_dwordx2 v[38:39], v[16:17], off offset:3168
	v_rcp_f32_e32 v41, v5
	v_mul_f32_e32 v5, 0xbfb8aa3b, v34
	v_and_b32_e32 v35, 0xffff0000, v35
	v_exp_f32_e32 v5, v5
	v_mul_f32_e32 v6, 0xbfb8aa3b, v35
	v_exp_f32_e32 v6, v6
	v_mov_b32_e32 v42, v46
	v_add_f32_e32 v5, 1.0, v5
	v_mov_b32_e32 v43, v44
	v_rcp_f32_e32 v46, v5
	v_add_f32_e32 v5, 1.0, v6
	v_pk_mul_f32 v[42:43], v[42:43], v[4:5] op_sel_hi:[1,0]
	v_mov_b32_e32 v44, v47
	v_rcp_f32_e32 v47, v5
	s_waitcnt vmcnt(1)
	v_pk_mul_f32 v[0:1], v[0:1], v[42:43]
	s_nop 0
	v_pk_mul_f32 v[0:1], v[0:1], v[36:37]
	v_pk_mul_f32 v[36:37], v[44:45], v[4:5] op_sel_hi:[1,0]
	v_pk_mul_f32 v[0:1], v[0:1], v[40:41]
	v_pk_mul_f32 v[2:3], v[2:3], v[36:37]
	v_cvt_pk_bf16_f32 v0, v0, v1
	v_pk_mul_f32 v[2:3], v[2:3], v[34:35]
	global_load_dwordx2 v[40:41], v[16:17], off offset:3200
	v_pk_mul_f32 v[2:3], v[2:3], v[46:47]
	s_waitcnt vmcnt(1)
	v_lshlrev_b32_e32 v34, 16, v38
	v_cvt_pk_bf16_f32 v1, v2, v3
	global_store_dwordx2 v[12:13], v[0:1], off offset:64
	global_load_dwordx4 v[0:3], v[160:161], off offset:192
	v_and_b32_e32 v35, 0xffff0000, v38
	v_mul_f32_e32 v5, 0xbfb8aa3b, v34
	v_exp_f32_e32 v5, v5
	v_mul_f32_e32 v6, 0xbfb8aa3b, v35
	v_exp_f32_e32 v6, v6
	v_lshlrev_b32_e32 v38, 16, v39
	v_add_f32_e32 v5, 1.0, v5
	v_rcp_f32_e32 v36, v5
	v_add_f32_e32 v5, 1.0, v6
	v_and_b32_e32 v39, 0xffff0000, v39
	v_mul_f32_e32 v6, 0xbfb8aa3b, v38
	v_exp_f32_e32 v6, v6
	v_mul_f32_e32 v8, 0xbfb8aa3b, v39
	v_exp_f32_e32 v8, v8
	v_rcp_f32_e32 v37, v5
	v_add_f32_e32 v5, 1.0, v6
	v_rcp_f32_e32 v42, v5
	v_add_f32_e32 v5, 1.0, v8
	v_rcp_f32_e32 v43, v5
	v_pk_mul_f32 v[26:27], v[26:27], v[4:5] op_sel_hi:[1,0]
	s_waitcnt vmcnt(0)
	v_pk_mul_f32 v[0:1], v[26:27], v[0:1]
	v_pk_mul_f32 v[26:27], v[28:29], v[4:5] op_sel_hi:[1,0]
	v_pk_mul_f32 v[0:1], v[0:1], v[34:35]
	v_pk_mul_f32 v[2:3], v[26:27], v[2:3]
	v_pk_mul_f32 v[0:1], v[0:1], v[36:37]
	v_pk_mul_f32 v[2:3], v[2:3], v[38:39]
	v_cvt_pk_bf16_f32 v0, v0, v1
	v_pk_mul_f32 v[2:3], v[2:3], v[42:43]
	v_lshlrev_b32_e32 v34, 16, v40
	v_cvt_pk_bf16_f32 v1, v2, v3
	global_store_dwordx2 v[12:13], v[0:1], off offset:96
	global_load_dwordx4 v[0:3], v[160:161], off offset:256
	s_nop 0
	global_load_dwordx2 v[26:27], v[16:17], off offset:3232
	v_and_b32_e32 v35, 0xffff0000, v40
	v_mul_f32_e32 v5, 0xbfb8aa3b, v34
	v_exp_f32_e32 v5, v5
	v_mul_f32_e32 v6, 0xbfb8aa3b, v35
	v_exp_f32_e32 v6, v6
	v_lshlrev_b32_e32 v28, 16, v41
	v_add_f32_e32 v5, 1.0, v5
	v_and_b32_e32 v29, 0xffff0000, v41
	v_rcp_f32_e32 v36, v5
	v_add_f32_e32 v5, 1.0, v6
	v_mul_f32_e32 v6, 0xbfb8aa3b, v28
	v_exp_f32_e32 v6, v6
	v_mul_f32_e32 v8, 0xbfb8aa3b, v29
	v_exp_f32_e32 v8, v8
	v_rcp_f32_e32 v37, v5
	v_add_f32_e32 v5, 1.0, v6
	v_rcp_f32_e32 v38, v5
	v_add_f32_e32 v5, 1.0, v8
	v_rcp_f32_e32 v39, v5
	v_pk_mul_f32 v[22:23], v[22:23], v[4:5] op_sel_hi:[1,0]
	s_waitcnt vmcnt(1)
; __device__ __forceinline__ float sigm(float x) { return __builtin_amdgcn_rcpf(1.0f + __expf(-x)); }
; __device__ __forceinline__ float lo16(unsigned w) { return __uint_as_float(w << 16); }
; __device__ __forceinline__ float hi16(unsigned w) { return __uint_as_float(w & 0xffff0000u); }
; __device__ __forceinline__ u32x2 pack4(float a, float b, float c, float d) { u32x2 w; w.x = cvt_pk_bf16(a, b); w.y = cvt_pk_bf16(c, d); return w; }
; __device__ void phase_hgrn_fix(const Ctx& p, int l, LAS unsigned char* lds) {
;     ...
; #pragma unroll
;             for (int vt = 0; vt < 8; ++vt) { const u32x2 gw = *(const u32x2*)(gp + vt * 16); const float4 n4 = *(const float4*)(nw + h * 128 + vt * 16 + 4 * fq);
;                 const float g4[4] = {lo16(gw.x), hi16(gw.x), lo16(gw.y), hi16(gw.y)}, nn[4] = {n4.x, n4.y, n4.z, n4.w}; float r[4];
; #pragma unroll
;                 for (int e = 0; e < 4; ++e) r[e] = o[vt][e] * rs * nn[e] * g4[e] * sigm(g4[e]);
;                 *(u32x2*)(YB + (size_t)t * 512 + h * 128 + vt * 16 + 4 * fq) = pack4(r[0], r[1], r[2], r[3]); }
	v_pk_mul_f32 v[0:1], v[22:23], v[0:1]
	v_pk_mul_f32 v[22:23], v[32:33], v[4:5] op_sel_hi:[1,0]
	v_pk_mul_f32 v[0:1], v[0:1], v[34:35]
	v_pk_mul_f32 v[2:3], v[22:23], v[2:3]
	v_pk_mul_f32 v[0:1], v[0:1], v[36:37]
	v_pk_mul_f32 v[2:3], v[2:3], v[28:29]
	v_cvt_pk_bf16_f32 v0, v0, v1
	v_pk_mul_f32 v[2:3], v[2:3], v[38:39]
	s_waitcnt vmcnt(0)
	v_lshlrev_b32_e32 v32, 16, v26
	v_cvt_pk_bf16_f32 v1, v2, v3
	global_store_dwordx2 v[12:13], v[0:1], off offset:128
	global_load_dwordx4 v[0:3], v[160:161], off offset:320
	s_nop 0
	global_load_dwordx2 v[22:23], v[16:17], off offset:3264
	v_and_b32_e32 v33, 0xffff0000, v26
	v_mul_f32_e32 v5, 0xbfb8aa3b, v32
	v_exp_f32_e32 v5, v5
	v_mul_f32_e32 v6, 0xbfb8aa3b, v33
	v_exp_f32_e32 v6, v6
	v_lshlrev_b32_e32 v28, 16, v27
	v_add_f32_e32 v5, 1.0, v5
	v_rcp_f32_e32 v26, v5
	v_add_f32_e32 v5, 1.0, v6
	v_and_b32_e32 v29, 0xffff0000, v27
	v_rcp_f32_e32 v27, v5
	v_pk_mul_f32 v[30:31], v[30:31], v[4:5] op_sel_hi:[1,0]
	v_mul_f32_e32 v5, 0xbfb8aa3b, v28
	v_exp_f32_e32 v5, v5
	v_mul_f32_e32 v6, 0xbfb8aa3b, v29
	v_exp_f32_e32 v6, v6
	v_add_f32_e32 v5, 1.0, v5
	s_waitcnt vmcnt(1)
	v_pk_mul_f32 v[0:1], v[30:31], v[0:1]
	s_nop 0
	v_pk_mul_f32 v[0:1], v[0:1], v[32:33]
	s_nop 0
	v_pk_mul_f32 v[0:1], v[0:1], v[26:27]
	v_rcp_f32_e32 v26, v5
	v_add_f32_e32 v5, 1.0, v6
	v_rcp_f32_e32 v27, v5
	v_pk_mul_f32 v[24:25], v[24:25], v[4:5] op_sel_hi:[1,0]
	v_cvt_pk_bf16_f32 v0, v0, v1
	v_pk_mul_f32 v[2:3], v[24:25], v[2:3]
	s_waitcnt vmcnt(0)
	v_lshlrev_b32_e32 v24, 16, v22
	v_pk_mul_f32 v[2:3], v[2:3], v[28:29]
	v_mul_f32_e32 v5, 0xbfb8aa3b, v24
	v_pk_mul_f32 v[2:3], v[2:3], v[26:27]
	v_and_b32_e32 v25, 0xffff0000, v22
	v_cvt_pk_bf16_f32 v1, v2, v3
	global_store_dwordx2 v[12:13], v[0:1], off offset:160
	global_load_dwordx4 v[0:3], v[160:161], off offset:384
	s_nop 0
	global_load_dwordx2 v[16:17], v[16:17], off offset:3296
	v_exp_f32_e32 v5, v5
	v_mul_f32_e32 v6, 0xbfb8aa3b, v25
	v_exp_f32_e32 v6, v6
	v_add_f32_e32 v5, 1.0, v5
	v_rcp_f32_e32 v26, v5
	v_add_f32_e32 v5, 1.0, v6
	v_pk_mul_f32 v[20:21], v[20:21], v[4:5] op_sel_hi:[1,0]
	v_rcp_f32_e32 v27, v5
	s_waitcnt vmcnt(1)
	v_pk_mul_f32 v[0:1], v[20:21], v[0:1]
	v_lshlrev_b32_e32 v20, 16, v23
	v_mul_f32_e32 v5, 0xbfb8aa3b, v20
	v_and_b32_e32 v21, 0xffff0000, v23
	v_exp_f32_e32 v5, v5
	v_mul_f32_e32 v6, 0xbfb8aa3b, v21
	v_exp_f32_e32 v6, v6
	v_pk_mul_f32 v[0:1], v[0:1], v[24:25]
	v_add_f32_e32 v5, 1.0, v5
	v_rcp_f32_e32 v22, v5
	v_add_f32_e32 v5, 1.0, v6
	v_rcp_f32_e32 v23, v5
	v_pk_mul_f32 v[18:19], v[18:19], v[4:5] op_sel_hi:[1,0]
	v_pk_mul_f32 v[0:1], v[0:1], v[26:27]
	v_pk_mul_f32 v[2:3], v[18:19], v[2:3]
	v_cvt_pk_bf16_f32 v0, v0, v1
	v_pk_mul_f32 v[2:3], v[2:3], v[20:21]
	s_waitcnt vmcnt(0)
	v_lshlrev_b32_e32 v18, 16, v16
	v_pk_mul_f32 v[2:3], v[2:3], v[22:23]
	v_mul_f32_e32 v5, 0xbfb8aa3b, v18
	v_cvt_pk_bf16_f32 v1, v2, v3
	global_store_dwordx2 v[12:13], v[0:1], off offset:192
	global_load_dwordx4 v[0:3], v[160:161], off offset:448
	v_and_b32_e32 v19, 0xffff0000, v16
	v_exp_f32_e32 v5, v5
	v_mul_f32_e32 v6, 0xbfb8aa3b, v19
	v_exp_f32_e32 v6, v6
	v_add_f32_e32 v5, 1.0, v5
	v_rcp_f32_e32 v8, v5
	v_add_f32_e32 v5, 1.0, v6
	v_rcp_f32_e32 v9, v5
	v_pk_mul_f32 v[10:11], v[10:11], v[4:5] op_sel_hi:[1,0]
	s_waitcnt vmcnt(0)
	v_pk_mul_f32 v[0:1], v[10:11], v[0:1]
	s_nop 0
	v_pk_mul_f32 v[0:1], v[0:1], v[18:19]
	s_nop 0
	v_pk_mul_f32 v[0:1], v[0:1], v[8:9]
	v_lshlrev_b32_e32 v8, 16, v17
	v_mul_f32_e32 v5, 0xbfb8aa3b, v8
	v_and_b32_e32 v9, 0xffff0000, v17
	v_exp_f32_e32 v5, v5
	v_mul_f32_e32 v6, 0xbfb8aa3b, v9
	v_exp_f32_e32 v11, v6
	v_mov_b32_e32 v6, v15
	v_add_f32_e32 v5, 1.0, v5
	v_rcp_f32_e32 v10, v5
	v_add_f32_e32 v5, 1.0, v11
	v_rcp_f32_e32 v11, v5
	v_pk_mul_f32 v[4:5], v[6:7], v[4:5] op_sel_hi:[1,0]
	v_cvt_pk_bf16_f32 v0, v0, v1
	v_pk_mul_f32 v[2:3], v[4:5], v[2:3]
	s_nop 0
	v_pk_mul_f32 v[2:3], v[2:3], v[8:9]
	s_nop 0
	v_pk_mul_f32 v[2:3], v[2:3], v[10:11]
	s_nop 0
	v_cvt_pk_bf16_f32 v1, v2, v3
	global_store_dwordx2 v[12:13], v[0:1], off offset:224
	s_cbranch_scc0 .LBB0_437
; __device__ __forceinline__ int bidx() { int b = blockIdx.x; asm volatile("" : "+s"(b)); return b; }
; __device__ __forceinline__ float bf2f(unsigned short b) { return __uint_as_float((unsigned)b << 16); }
; __device__ __forceinline__ unsigned short f2bf(float f) { unsigned u = __float_as_uint(f); u += 0x7FFFu + ((u >> 16) & 1u); return (unsigned short)(u >> 16); }
; __device__ __forceinline__ float sigm(float x) { return __builtin_amdgcn_rcpf(1.0f + __expf(-x)); }
; __device__ void phase_hgrn_fix(const Ctx& p, int l, LAS unsigned char* lds) {
;     ...
;     if (wave == 0) {
;         for (int item = bidx(); item < 128; item += gridDim.x) {
;             const int s = item >> 2, h = item & 3;
;             const float nw0 = nw[h * 128 + lane], nw1 = nw[h * 128 + 64 + lane];
; #pragma unroll 4
;             for (int tt = 0; tt < 32; ++tt) {
;                 const int t = T_P + s * 32 + tt;
;                 const float o0 = bf2f(OH[(size_t)t * 512 + h * 128 + lane]) + bf2f(OH1[(size_t)t * 512 + h * 128 + lane]), o1 = bf2f(OH[(size_t)t * 512 + h * 128 + 64 + lane]) + bf2f(OH1[(size_t)t * 512 + h * 128 + 64 + lane]);
;                 const float g0 = bf2f(PH[(size_t)t * 2048 + 1536 + h * 128 + lane]), g1 = bf2f(PH[(size_t)t * 2048 + 1536 + h * 128 + 64 + lane]);
;                 const float rs = rsqrtf(wsum_fast(o0 * o0 + o1 * o1) * (1.0f / 128.0f) + 1e-6f);
;                 YB[(size_t)t * 512 + h * 128 + lane] = f2bf(o0 * rs * nw0 * g0 * sigm(g0));
;                 YB[(size_t)t * 512 + h * 128 + 64 + lane] = f2bf(o1 * rs * nw1 * g1 * sigm(g1));
;             }
;         }
;     }
.LBB0_447:
	v_readlane_b32 s39, v242, 28
	s_mov_b32 s38, 0x1ffff
	v_readfirstlane_b32 s0, v184
	s_lshr_b32 s0, s0, 6
	s_lshl_b32 s1, s90, 3
	s_add_i32 s0, s0, s1
	s_cmpk_gt_u32 s0, 0x7ff
	s_cbranch_scc1 .LBB0_453
	s_lshl_b32 s0, s0, 1
	s_lshr_b32 s1, s0, 7
	s_lshl_b32 s1, s1, 5
	s_and_b32 s2, s0, 31
	s_add_i32 s1, s1, s2
	s_bfe_u32 s2, s0, 0x20005
	s_lshl_b32 s2, s2, 7
	v_add_u32_e32 v0, s2, v116
	v_lshlrev_b32_e32 v1, 2, v0
	v_lshlrev_b32_e32 v0, 1, v0
	s_lshl_b32 s3, s1, 10
	v_add_u32_e32 v2, s3, v0
	s_lshl_b32 s3, s1, 12
	v_add_u32_e32 v3, s3, v0
	v_add_u32_e32 v4, 0x1000, v3
	s_add_u32 s4, s20, 0xcb00000
	s_addc_u32 s5, s21, 0
	s_add_u32 s6, s20, 0xfe00000
	s_addc_u32 s7, s21, 0
	s_add_u32 s12, s20, 0x9500000
	s_addc_u32 s13, s21, 0
	s_add_u32 s2, s20, 0xba00000
	s_addc_u32 s3, s21, 0
	global_load_dword v8, v1, s[22:23]
	global_load_dword v9, v1, s[22:23] offset:256
	global_load_ushort v10, v3, s[12:13] offset:3072
	global_load_ushort v11, v3, s[12:13] offset:3200
	global_load_ushort v12, v2, s[4:5]
	global_load_ushort v13, v2, s[4:5] offset:128
	global_load_ushort v14, v2, s[6:7]
	global_load_ushort v15, v2, s[6:7] offset:128
	global_load_ushort v16, v4, s[12:13] offset:3072
	global_load_ushort v17, v4, s[12:13] offset:3200
	global_load_ushort v18, v2, s[4:5] offset:1024
	global_load_ushort v19, v2, s[4:5] offset:1152
	global_load_ushort v20, v2, s[6:7] offset:1024
	global_load_ushort v21, v2, s[6:7] offset:1152
	s_waitcnt vmcnt(6)
	v_lshlrev_b32_e32 v10, 16, v10
	v_lshlrev_b32_e32 v11, 16, v11
	v_lshlrev_b32_e32 v12, 16, v12
	v_lshlrev_b32_e32 v13, 16, v13
	v_lshlrev_b32_e32 v14, 16, v14
	v_lshlrev_b32_e32 v15, 16, v15
	v_add_f32_e32 v12, v12, v14
	v_add_f32_e32 v13, v13, v15
	v_mul_f32_e32 v22, v12, v12
	v_mul_f32_e32 v23, v13, v13
	v_add_f32_e32 v22, v22, v23
	s_nop 1
	v_add_f32_dpp v22, v22, v22 quad_perm:[1,0,3,2] row_mask:0xf bank_mask:0xf bound_ctrl:1
	s_nop 1
	v_add_f32_dpp v22, v22, v22 quad_perm:[2,3,0,1] row_mask:0xf bank_mask:0xf bound_ctrl:1
	s_nop 1
	v_add_f32_dpp v22, v22, v22 row_half_mirror row_mask:0xf bank_mask:0xf bound_ctrl:1
	s_nop 1
	v_add_f32_dpp v22, v22, v22 row_mirror row_mask:0xf bank_mask:0xf bound_ctrl:1
	s_nop 0
	v_readlane_b32 s12, v22, 16
	v_readlane_b32 s10, v22, 0
	s_nop 0
	v_mov_b32_e32 v23, s12
	v_add_f32_e32 v23, s10, v23
	v_readlane_b32 s10, v22, 32
	s_nop 1
	v_add_f32_e32 v23, s10, v23
	v_readlane_b32 s10, v22, 48
	s_nop 1
	v_add_f32_e32 v22, s10, v23
	v_fmamk_f32 v22, v22, 0x3c000000, v187
	v_cmp_gt_f32_e32 vcc, s67, v22
	v_mul_f32_e32 v23, 0x4b800000, v22
	s_nop 0
	v_cndmask_b32_e32 v22, v22, v23, vcc
	v_rsq_f32_e32 v22, v22
	s_nop 0
	v_mul_f32_e32 v23, 0x45800000, v22
	v_cndmask_b32_e32 v22, v22, v23, vcc
	v_mul_f32_e32 v23, 0xbfb8aa3b, v10
	v_exp_f32_e32 v23, v23
	v_mul_f32_e32 v12, v12, v22
	v_mul_f32_e32 v12, v8, v12
	v_mul_f32_e32 v12, v12, v10
	v_add_f32_e32 v23, 1.0, v23
	v_rcp_f32_e32 v23, v23
	s_nop 0
	v_mul_f32_e32 v12, v23, v12
	v_bfe_u32 v23, v12, 16, 1
	v_add3_u32 v12, v12, v23, s69
	global_store_short_d16_hi v2, v12, s[2:3]
	v_mul_f32_e32 v23, 0xbfb8aa3b, v11
	v_exp_f32_e32 v23, v23
	v_mul_f32_e32 v13, v13, v22
	v_mul_f32_e32 v13, v9, v13
	v_mul_f32_e32 v13, v13, v11
	v_add_f32_e32 v23, 1.0, v23
	v_rcp_f32_e32 v23, v23
	s_nop 0
	v_mul_f32_e32 v13, v23, v13
	v_bfe_u32 v23, v13, 16, 1
	v_add3_u32 v13, v13, v23, s69
	global_store_short_d16_hi v2, v13, s[2:3] offset:128
	s_waitcnt vmcnt(2)
	v_lshlrev_b32_e32 v16, 16, v16
	v_lshlrev_b32_e32 v17, 16, v17
	v_lshlrev_b32_e32 v18, 16, v18
	v_lshlrev_b32_e32 v19, 16, v19
	v_lshlrev_b32_e32 v20, 16, v20
	v_lshlrev_b32_e32 v21, 16, v21
	v_add_f32_e32 v18, v18, v20
	v_add_f32_e32 v19, v19, v21
	v_mul_f32_e32 v22, v18, v18
	v_mul_f32_e32 v23, v19, v19
	v_add_f32_e32 v22, v22, v23
	s_nop 1
	v_add_f32_dpp v22, v22, v22 quad_perm:[1,0,3,2] row_mask:0xf bank_mask:0xf bound_ctrl:1
	s_nop 1
	v_add_f32_dpp v22, v22, v22 quad_perm:[2,3,0,1] row_mask:0xf bank_mask:0xf bound_ctrl:1
	s_nop 1
	v_add_f32_dpp v22, v22, v22 row_half_mirror row_mask:0xf bank_mask:0xf bound_ctrl:1
	s_nop 1
	v_add_f32_dpp v22, v22, v22 row_mirror row_mask:0xf bank_mask:0xf bound_ctrl:1
	s_nop 0
	v_readlane_b32 s12, v22, 16
	v_readlane_b32 s10, v22, 0
	s_nop 0
	v_mov_b32_e32 v23, s12
	v_add_f32_e32 v23, s10, v23
	v_readlane_b32 s10, v22, 32
	s_nop 1
	v_add_f32_e32 v23, s10, v23
	v_readlane_b32 s10, v22, 48
	s_nop 1
	v_add_f32_e32 v22, s10, v23
	v_fmamk_f32 v22, v22, 0x3c000000, v187
	v_cmp_gt_f32_e32 vcc, s67, v22
	v_mul_f32_e32 v23, 0x4b800000, v22
	s_nop 0
	v_cndmask_b32_e32 v22, v22, v23, vcc
	v_rsq_f32_e32 v22, v22
	s_nop 0
	v_mul_f32_e32 v23, 0x45800000, v22
	v_cndmask_b32_e32 v22, v22, v23, vcc
	v_mul_f32_e32 v23, 0xbfb8aa3b, v16
	v_exp_f32_e32 v23, v23
	v_mul_f32_e32 v18, v18, v22
	v_mul_f32_e32 v18, v8, v18
	v_mul_f32_e32 v18, v18, v16
	v_add_f32_e32 v23, 1.0, v23
	v_rcp_f32_e32 v23, v23
	s_nop 0
	v_mul_f32_e32 v18, v23, v18
	v_bfe_u32 v23, v18, 16, 1
	v_add3_u32 v18, v18, v23, s69
	global_store_short_d16_hi v2, v18, s[2:3] offset:1024
	v_mul_f32_e32 v23, 0xbfb8aa3b, v17
	v_exp_f32_e32 v23, v23
	v_mul_f32_e32 v19, v19, v22
	v_mul_f32_e32 v19, v9, v19
	v_mul_f32_e32 v19, v19, v17
	v_add_f32_e32 v23, 1.0, v23
	v_rcp_f32_e32 v23, v23
	s_nop 0
	v_mul_f32_e32 v19, v23, v19
	v_bfe_u32 v23, v19, 16, 1
	v_add3_u32 v19, v19, v23, s69
	global_store_short_d16_hi v2, v19, s[2:3] offset:1152
